# U sweep gathers as structured buffer loads (index = expert id, stride 1024, offset = 16*lane): no per-row address VALU; ids read into (id, offset) register pairs; on top of v062
# baseline (speedup 1.0000x reference)
.LBB0_88:
	s_andn2_saveexec_b64 s[0:1], s[0:1]
	v_mov_b32_e32 v22, s53
	v_add_f32_e32 v22, s49, v22
	v_add_f32_e32 v34, s52, v22
	s_or_b64 exec, exec, s[0:1]
	v_add_u32_e32 v35, 0x3000, v21
	v_max_f32_e64 v21, s48, s48
	v_max_f32_e64 v22, s44, s44
	v_max_f32_e32 v21, v22, v21
	v_max_f32_e64 v22, s45, s45
	v_max_f32_e64 v23, s95, s95
	v_max_f32_e32 v22, v23, v22
	s_mov_b32 s12, 0x1e3ce508
	v_max3_f32 v21, v21, v22, s12
	s_mov_b32 s13, 0x43700000
	v_div_scale_f32 v22, s[0:1], v21, v21, s13
	v_rcp_f32_e32 v23, v22
	v_readlane_b32 s0, v254, 10
	v_add_u32_e32 v20, 0x3000, v20
	v_readlane_b32 s1, v254, 11
	v_fma_f32 v55, -v22, v23, 1.0
	v_fmac_f32_e32 v23, v55, v23
	v_div_scale_f32 v55, vcc, s13, v21, s13
	v_mul_f32_e32 v128, v55, v23
	v_fma_f32 v187, -v22, v128, v55
	v_fmac_f32_e32 v128, v187, v23
	v_fma_f32 v22, -v22, v128, v55
	v_div_fmas_f32 v22, v22, v23, v128
	v_div_fixup_f32 v22, v22, v21, s13
	v_mul_f32_e32 v128, 0x3b888889, v21
	v_mul_f32_e32 v21, v22, v94
	v_mul_f32_e32 v23, v22, v186
	v_mov_b32_e32 v94, v155
	v_cvt_pk_fp8_f32 v94, v21, v23
	v_mul_f32_e32 v21, v22, v184
	v_mul_f32_e32 v23, v22, v185
	v_cmp_ne_u32_e32 vcc, -1, v20
	v_cvt_pk_fp8_f32 v94, v21, v23 op_sel:[0,0,1]
	v_mul_f32_e32 v21, v22, v95
	v_mul_f32_e32 v23, v22, v175
	v_mov_b32_e32 v95, v155
	v_cvt_pk_fp8_f32 v95, v21, v23
	v_mul_f32_e32 v21, v22, v173
	v_mul_f32_e32 v23, v22, v174
	v_max_f32_e64 v55, s60, s60
	v_cvt_pk_fp8_f32 v95, v21, v23 op_sel:[0,0,1]
	v_mul_f32_e32 v21, v22, v96
	v_mul_f32_e32 v23, v22, v170
	v_mov_b32_e32 v96, v155
	v_cvt_pk_fp8_f32 v96, v21, v23
	v_mul_f32_e32 v21, v22, v171
	v_mul_f32_e32 v23, v22, v172
	s_mov_b32 s95, 0
	v_cvt_pk_fp8_f32 v96, v21, v23 op_sel:[0,0,1]
	v_mul_f32_e32 v21, v22, v97
	v_mul_f32_e32 v23, v22, v169
	v_mov_b32_e32 v97, v155
	v_cvt_pk_fp8_f32 v97, v21, v23
	v_mul_f32_e32 v21, v22, v37
	v_mul_f32_e32 v22, v22, v129
	v_max_f32_e64 v37, s72, s72
	v_cvt_pk_fp8_f32 v97, v21, v22 op_sel:[0,0,1]
	v_mov_b32_e32 v21, s1
	v_cndmask_b32_e32 v23, 0, v21, vcc
	v_cndmask_b32_e32 v22, 0, v20, vcc
	v_cmp_ne_u32_e32 vcc, -1, v35
	s_nop 1
	v_cndmask_b32_e32 v20, 0, v35, vcc
	v_max_f32_e64 v35, s94, s94
	v_max_f32_e32 v35, v37, v35
	v_max_f32_e64 v37, s73, s73
	v_max_f32_e32 v37, v55, v37
	v_max3_f32 v35, v35, v37, s12
	v_div_scale_f32 v37, s[0:1], v35, v35, s13
	v_rcp_f32_e32 v55, v37
	v_cndmask_b32_e32 v21, 0, v21, vcc
	v_fma_f32 v129, -v37, v55, 1.0
	v_fmac_f32_e32 v55, v129, v55
	v_div_scale_f32 v129, vcc, s13, v35, s13
	v_mul_f32_e32 v169, v129, v55
	v_fma_f32 v170, -v37, v169, v129
	v_fmac_f32_e32 v169, v170, v55
	v_fma_f32 v37, -v37, v169, v129
	v_div_fmas_f32 v37, v37, v55, v169
	v_div_fixup_f32 v37, v37, v35, s13
	v_mul_f32_e32 v129, 0x3b888889, v35
	v_mul_f32_e32 v35, v37, v98
	v_mul_f32_e32 v55, v37, v168
	v_mov_b32_e32 v98, v155
	v_cvt_pk_fp8_f32 v98, v35, v55
	v_mul_f32_e32 v35, v37, v99
	v_mul_f32_e32 v55, v37, v163
	v_mov_b32_e32 v99, v155
	v_cvt_pk_fp8_f32 v98, v35, v55 op_sel:[0,0,1]
	v_mul_f32_e32 v35, v37, v164
	v_mul_f32_e32 v55, v37, v165
	v_cvt_pk_fp8_f32 v99, v35, v55
	v_mul_f32_e32 v35, v37, v166
	v_mul_f32_e32 v55, v37, v167
	v_cvt_pk_fp8_f32 v99, v35, v55 op_sel:[0,0,1]
	v_mul_f32_e32 v35, v37, v100
	v_mul_f32_e32 v55, v37, v162
	v_mov_b32_e32 v100, v155
	v_cvt_pk_fp8_f32 v100, v35, v55
	v_mul_f32_e32 v35, v37, v101
	v_mul_f32_e32 v55, v37, v136
	v_mov_b32_e32 v101, v155
	v_cvt_pk_fp8_f32 v100, v35, v55 op_sel:[0,0,1]
	v_mul_f32_e32 v35, v37, v153
	v_mul_f32_e32 v55, v37, v154
	v_cvt_pk_fp8_f32 v101, v35, v55
	v_mul_f32_e32 v35, v37, v160
	v_mul_f32_e32 v37, v37, v161
	v_max_f32_e64 v55, s17, s17
	v_cvt_pk_fp8_f32 v101, v35, v37 op_sel:[0,0,1]
	v_max_f32_e64 v35, s19, s19
	v_max_f32_e64 v37, s75, s75
	v_max_f32_e32 v35, v37, v35
	v_max_f32_e64 v37, s18, s18
	v_max_f32_e32 v37, v55, v37
	v_max3_f32 v35, v35, v37, s12
	v_div_scale_f32 v37, s[0:1], v35, v35, s13
	v_rcp_f32_e32 v55, v37
	s_nop 0
	v_fma_f32 v136, -v37, v55, 1.0
	v_fmac_f32_e32 v55, v136, v55
	v_div_scale_f32 v136, vcc, s13, v35, s13
	v_mul_f32_e32 v153, v136, v55
	v_fma_f32 v154, -v37, v153, v136
	v_fmac_f32_e32 v153, v154, v55
	v_fma_f32 v37, -v37, v153, v136
	v_div_fmas_f32 v37, v37, v55, v153
	v_div_fixup_f32 v37, v37, v35, s13
	v_mul_f32_e32 v136, 0x3b888889, v35
	v_mul_f32_e32 v35, v37, v102
	v_mul_f32_e32 v55, v37, v152
	v_mov_b32_e32 v102, v155
	v_cvt_pk_fp8_f32 v102, v35, v55
	v_mul_f32_e32 v35, v37, v103
	v_mul_f32_e32 v55, v37, v147
	v_mov_b32_e32 v103, v155
	v_cvt_pk_fp8_f32 v102, v35, v55 op_sel:[0,0,1]
	v_mul_f32_e32 v35, v37, v148
	v_mul_f32_e32 v55, v37, v149
	v_cvt_pk_fp8_f32 v103, v35, v55
	v_mul_f32_e32 v35, v37, v150
	v_mul_f32_e32 v55, v37, v151
	v_cvt_pk_fp8_f32 v103, v35, v55 op_sel:[0,0,1]
	v_mul_f32_e32 v35, v37, v104
	v_mul_f32_e32 v55, v37, v146
	v_mov_b32_e32 v104, v155
	v_cvt_pk_fp8_f32 v104, v35, v55
	v_mul_f32_e32 v35, v37, v105
	v_mul_f32_e32 v55, v37, v137
	v_mov_b32_e32 v105, v155
	v_cvt_pk_fp8_f32 v104, v35, v55 op_sel:[0,0,1]
	v_mul_f32_e32 v35, v37, v142
	v_mul_f32_e32 v55, v37, v143
	v_cvt_pk_fp8_f32 v105, v35, v55
	v_mul_f32_e32 v35, v37, v144
	v_mul_f32_e32 v37, v37, v145
	v_max_f32_e64 v55, s31, s31
	v_cvt_pk_fp8_f32 v105, v35, v37 op_sel:[0,0,1]
	v_max_f32_e64 v35, s16, s16
	v_max_f32_e64 v37, s10, s10
	v_max_f32_e32 v35, v37, v35
	v_max_f32_e64 v37, s11, s11
	v_max_f32_e32 v37, v55, v37
	v_max3_f32 v35, v35, v37, s12
	v_div_scale_f32 v37, s[0:1], v35, v35, s13
	v_rcp_f32_e32 v55, v37
	s_bfe_i32 s10, s96, 0x10000
	v_fma_f32 v137, -v37, v55, 1.0
	v_fmac_f32_e32 v55, v137, v55
	v_div_scale_f32 v137, vcc, s13, v35, s13
	v_mul_f32_e32 v142, v137, v55
	v_fma_f32 v143, -v37, v142, v137
	v_fmac_f32_e32 v142, v143, v55
	v_fma_f32 v37, -v37, v142, v137
	v_div_fmas_f32 v37, v37, v55, v142
	v_div_fixup_f32 v37, v37, v35, s13
	v_mul_f32_e32 v137, 0x3b888889, v35
	v_mul_f32_e32 v35, v37, v106
	v_mul_f32_e32 v55, v37, v141
	v_mov_b32_e32 v106, v155
	v_cvt_pk_fp8_f32 v106, v35, v55
	v_mul_f32_e32 v35, v37, v107
	v_mul_f32_e32 v55, v37, v126
	v_mov_b32_e32 v107, v155
	v_cvt_pk_fp8_f32 v106, v35, v55 op_sel:[0,0,1]
	v_mul_f32_e32 v35, v37, v127
	v_mul_f32_e32 v55, v37, v138
	v_cvt_pk_fp8_f32 v107, v35, v55
	v_mul_f32_e32 v35, v37, v139
	v_mul_f32_e32 v55, v37, v140
	v_cvt_pk_fp8_f32 v107, v35, v55 op_sel:[0,0,1]
	v_mul_f32_e32 v35, v37, v108
	v_mul_f32_e32 v55, v37, v125
	v_mov_b32_e32 v108, v155
	v_cvt_pk_fp8_f32 v108, v35, v55
	v_mul_f32_e32 v35, v37, v109
	v_mul_f32_e32 v55, v37, v120
	v_mov_b32_e32 v109, v155
	v_cvt_pk_fp8_f32 v108, v35, v55 op_sel:[0,0,1]
	v_mul_f32_e32 v35, v37, v121
	v_mul_f32_e32 v55, v37, v122
	v_cvt_pk_fp8_f32 v109, v35, v55
	v_mul_f32_e32 v35, v37, v123
	v_mul_f32_e32 v37, v37, v124
	v_max_f32_e64 v55, s97, s97
	v_cvt_pk_fp8_f32 v109, v35, v37 op_sel:[0,0,1]
	v_max_f32_e64 v35, s30, s30
	v_max_f32_e64 v37, s20, s20
	v_max_f32_e32 v35, v37, v35
	v_max_f32_e64 v37, s21, s21
	v_max_f32_e32 v37, v55, v37
	v_max3_f32 v35, v35, v37, s12
	v_div_scale_f32 v37, s[0:1], v35, v35, s13
	v_rcp_f32_e32 v55, v37
	v_mul_f32_e32 v138, 0x3b888889, v35
	v_mov_b32_e32 v123, v155
	v_mov_b32_e32 v124, v155
	v_fma_f32 v120, -v37, v55, 1.0
	v_fmac_f32_e32 v55, v120, v55
	v_div_scale_f32 v120, vcc, s13, v35, s13
	v_mul_f32_e32 v121, v120, v55
	v_fma_f32 v122, -v37, v121, v120
	v_fmac_f32_e32 v121, v122, v55
	v_fma_f32 v37, -v37, v121, v120
	v_div_fmas_f32 v37, v37, v55, v121
	v_div_fixup_f32 v37, v37, v35, s13
	v_mul_f32_e32 v35, v37, v110
	v_mul_f32_e32 v55, v37, v119
	v_mov_b32_e32 v110, v155
	v_cvt_pk_fp8_f32 v110, v35, v55
	v_mul_f32_e32 v35, v37, v111
	v_mul_f32_e32 v55, v37, v114
	v_mov_b32_e32 v111, v155
	v_cvt_pk_fp8_f32 v110, v35, v55 op_sel:[0,0,1]
	v_mul_f32_e32 v35, v37, v115
	v_mul_f32_e32 v55, v37, v116
	v_cvt_pk_fp8_f32 v111, v35, v55
	v_mul_f32_e32 v35, v37, v117
	v_mul_f32_e32 v55, v37, v118
	v_mov_b32_e32 v114, v155
	v_cvt_pk_fp8_f32 v111, v35, v55 op_sel:[0,0,1]
	v_mul_f32_e32 v35, v37, v112
	v_mul_f32_e32 v55, v37, v113
	v_mov_b32_e32 v112, v155
	v_cvt_pk_fp8_f32 v112, v35, v55
	v_mul_f32_e32 v35, v37, v88
	v_mul_f32_e32 v55, v37, v89
	v_mov_b32_e32 v113, v155
	v_cvt_pk_fp8_f32 v112, v35, v55 op_sel:[0,0,1]
	v_mul_f32_e32 v35, v37, v90
	v_mul_f32_e32 v55, v37, v91
	v_cvt_pk_fp8_f32 v113, v35, v55
	v_mul_f32_e32 v35, v37, v92
	v_mul_f32_e32 v37, v37, v93
	v_max_f32_e64 v55, s90, s90
	v_cvt_pk_fp8_f32 v113, v35, v37 op_sel:[0,0,1]
	v_max_f32_e64 v35, s92, s92
	v_max_f32_e64 v37, s74, s74
	v_max_f32_e32 v35, v37, v35
	v_max_f32_e64 v37, s91, s91
	v_max_f32_e32 v37, v55, v37
	v_max3_f32 v35, v35, v37, s12
	v_div_scale_f32 v37, s[0:1], v35, v35, s13
	v_rcp_f32_e32 v55, v37
	v_mul_f32_e32 v139, 0x3b888889, v35
	v_mov_b32_e32 v115, v155
	v_mov_b32_e32 v116, v155
	v_fma_f32 v88, -v37, v55, 1.0
	v_fmac_f32_e32 v55, v88, v55
	v_div_scale_f32 v88, vcc, s13, v35, s13
	v_mul_f32_e32 v89, v88, v55
	v_fma_f32 v90, -v37, v89, v88
	v_fmac_f32_e32 v89, v90, v55
	v_fma_f32 v37, -v37, v89, v88
	v_div_fmas_f32 v37, v37, v55, v89
	v_div_fixup_f32 v37, v37, v35, s13
	v_mul_f32_e32 v35, v37, v80
	v_mul_f32_e32 v55, v37, v81
	v_cvt_pk_fp8_f32 v114, v35, v55
	v_mul_f32_e32 v35, v37, v82
	v_mul_f32_e32 v55, v37, v83
	v_mov_b32_e32 v117, v155
	v_cvt_pk_fp8_f32 v114, v35, v55 op_sel:[0,0,1]
	v_mul_f32_e32 v35, v37, v84
	v_mul_f32_e32 v55, v37, v85
	v_cvt_pk_fp8_f32 v115, v35, v55
	v_mul_f32_e32 v35, v37, v86
	v_mul_f32_e32 v55, v37, v87
	v_readlane_b32 s0, v254, 44
	v_cvt_pk_fp8_f32 v115, v35, v55 op_sel:[0,0,1]
	v_mul_f32_e32 v35, v37, v72
	v_mul_f32_e32 v55, v37, v73
	v_cvt_pk_fp8_f32 v116, v35, v55
	v_mul_f32_e32 v35, v37, v74
	v_mul_f32_e32 v55, v37, v75
	v_mov_b32_e32 v118, v155
	v_cvt_pk_fp8_f32 v116, v35, v55 op_sel:[0,0,1]
	v_mul_f32_e32 v35, v37, v76
	v_mul_f32_e32 v55, v37, v77
	v_cvt_pk_fp8_f32 v117, v35, v55
	v_mul_f32_e32 v35, v37, v78
	v_mul_f32_e32 v37, v37, v79
	v_max_f32_e64 v55, s0, s0
	v_cvt_pk_fp8_f32 v117, v35, v37 op_sel:[0,0,1]
	v_max_f32_e64 v35, s37, s37
	v_max_f32_e64 v37, s35, s35
	v_max_f32_e32 v35, v37, v35
	v_max_f32_e64 v37, s36, s36
	v_max_f32_e32 v37, v55, v37
	v_max3_f32 v35, v35, v37, s12
	v_div_scale_f32 v37, s[0:1], v35, v35, s13
	v_rcp_f32_e32 v55, v37
	v_mul_f32_e32 v140, 0x3b888889, v35
	v_mov_b32_e32 v119, v155
	v_mov_b32_e32 v120, v155
	v_fma_f32 v72, -v37, v55, 1.0
	v_fmac_f32_e32 v55, v72, v55
	v_div_scale_f32 v72, vcc, s13, v35, s13
	v_mul_f32_e32 v73, v72, v55
	v_fma_f32 v74, -v37, v73, v72
	v_fmac_f32_e32 v73, v74, v55
	v_fma_f32 v37, -v37, v73, v72
	v_div_fmas_f32 v37, v37, v55, v73
	v_div_fixup_f32 v37, v37, v35, s13
	v_mul_f32_e32 v35, v37, v64
	v_mul_f32_e32 v55, v37, v65
	v_cvt_pk_fp8_f32 v118, v35, v55
	v_mul_f32_e32 v35, v37, v66
	v_mul_f32_e32 v55, v37, v67
	v_mov_b32_e32 v121, v155
	v_cvt_pk_fp8_f32 v118, v35, v55 op_sel:[0,0,1]
	v_mul_f32_e32 v35, v37, v68
	v_mul_f32_e32 v55, v37, v69
	v_cvt_pk_fp8_f32 v119, v35, v55
	v_mul_f32_e32 v35, v37, v70
	v_mul_f32_e32 v55, v37, v71
	v_readlane_b32 s0, v254, 42
	v_cvt_pk_fp8_f32 v119, v35, v55 op_sel:[0,0,1]
	v_mul_f32_e32 v35, v37, v56
	v_mul_f32_e32 v55, v37, v57
	v_cvt_pk_fp8_f32 v120, v35, v55
	v_mul_f32_e32 v35, v37, v58
	v_mul_f32_e32 v55, v37, v59
	v_mov_b32_e32 v122, v155
	v_cvt_pk_fp8_f32 v120, v35, v55 op_sel:[0,0,1]
	v_mul_f32_e32 v35, v37, v60
	v_mul_f32_e32 v55, v37, v61
	v_cvt_pk_fp8_f32 v121, v35, v55
	v_mul_f32_e32 v35, v37, v62
	v_mul_f32_e32 v37, v37, v63
	v_mov_b32_e32 v125, v155
	v_cvt_pk_fp8_f32 v121, v35, v37 op_sel:[0,0,1]
	v_max_f32_e64 v35, s0, s0
	v_readlane_b32 s0, v254, 38
	s_mov_b32 s36, 30
	s_nop 0
	v_max_f32_e64 v37, s0, s0
	v_readlane_b32 s0, v254, 40
	v_max_f32_e32 v35, v37, v35
	s_nop 0
	v_max_f32_e64 v37, s0, s0
	v_readlane_b32 s0, v254, 36
	s_nop 1
	v_max_f32_e64 v55, s0, s0
	v_max_f32_e32 v37, v55, v37
	v_max3_f32 v35, v35, v37, s12
	v_div_scale_f32 v37, s[0:1], v35, v35, s13
	v_rcp_f32_e32 v55, v37
	v_mul_f32_e32 v141, 0x3b888889, v35
	s_and_b32 s0, s96, 1
	s_cmp_eq_u32 s0, 0
	v_fma_f32 v56, -v37, v55, 1.0
	v_fmac_f32_e32 v55, v56, v55
	v_div_scale_f32 v56, vcc, s13, v35, s13
	v_mul_f32_e32 v57, v56, v55
	v_fma_f32 v58, -v37, v57, v56
	v_fmac_f32_e32 v57, v58, v55
	v_fma_f32 v37, -v37, v57, v56
	v_div_fmas_f32 v37, v37, v55, v57
	v_div_fixup_f32 v37, v37, v35, s13
	v_mul_f32_e32 v35, v37, v47
	v_mul_f32_e32 v47, v37, v48
	v_cvt_pk_fp8_f32 v122, v35, v47
	v_mul_f32_e32 v35, v37, v49
	v_mul_f32_e32 v47, v37, v50
	v_mul_f32_e32 v1, v37, v1
	v_cvt_pk_fp8_f32 v122, v35, v47 op_sel:[0,0,1]
	v_mul_f32_e32 v35, v37, v51
	v_mul_f32_e32 v47, v37, v52
	v_cvt_pk_fp8_f32 v123, v35, v47
	v_mul_f32_e32 v35, v37, v53
	v_mul_f32_e32 v47, v37, v54
	s_cselect_b64 s[0:1], -1, 0
	v_cvt_pk_fp8_f32 v123, v35, v47 op_sel:[0,0,1]
	v_mul_f32_e32 v35, v37, v40
	v_cvt_pk_fp8_f32 v124, v1, v35
	v_mul_f32_e32 v1, v37, v41
	v_mul_f32_e32 v35, v37, v42
	s_and_b32 s34, s10, 31
	v_cvt_pk_fp8_f32 v124, v1, v35 op_sel:[0,0,1]
	v_mul_f32_e32 v1, v37, v43
	v_mul_f32_e32 v35, v37, v44
	v_cvt_pk_fp8_f32 v125, v1, v35
	v_mul_f32_e32 v1, v37, v45
	v_mul_f32_e32 v35, v37, v46
	v_ashrrev_i32_e32 v37, 31, v36
	v_cvt_pk_fp8_f32 v125, v1, v35 op_sel:[0,0,1]
	v_add_f32_e32 v1, v33, v34
	v_cvt_u32_f32_e32 v1, v1
	s_lshl_b32 s35, s34, 4
	s_add_i32 s10, s93, s35
	v_mov_b32_e32 v62, s10
	v_sub_u32_e32 v1, v1, v32
	ds_write_b32 v2, v1
	v_add_u32_e32 v1, v1, v26
	ds_write_b32 v4, v1
	v_add_u32_e32 v1, v1, v25
	ds_write_b32 v6, v1
	v_add_u32_e32 v1, v1, v28
	ds_write_b32 v8, v1
	v_add_u32_e32 v1, v1, v27
	ds_write_b32 v10, v1
	v_add_u32_e32 v1, v1, v30
	ds_write_b32 v12, v1
	v_add_u32_e32 v1, v1, v29
	ds_write_b32 v14, v1
	v_add_u32_e32 v1, v1, v31
	ds_write_b32 v16, v1
	s_waitcnt lgkmcnt(0)
	ds_read_b32 v1, v22
	ds_read_b32 v2, v20
	s_waitcnt lgkmcnt(0)
	v_lshl_add_u64 v[4:5], v[36:37], 3, s[28:29]
	global_load_dwordx2 v[4:5], v[4:5], off
	s_waitcnt lgkmcnt(0)
	v_add_u32_e32 v1, v1, v19
	v_ashrrev_i32_e32 v19, 31, v18
	v_add_u32_e32 v6, v2, v24
	v_lshl_add_u64 v[2:3], v[18:19], 3, s[28:29]
	global_load_dwordx2 v[2:3], v[2:3], off
	v_lshl_add_u32 v1, v1, 2, s93
	s_waitcnt vmcnt(0)
	v_mul_f32_e32 v3, v38, v3
	ds_write2st64_b32 v1, v18, v3 offset0:42 offset1:44
	ds_write_b32 v1, v2 offset:11776
	v_lshl_add_u32 v1, v6, 2, s93
	v_mul_f32_e32 v2, v39, v5
	ds_write2st64_b32 v1, v36, v2 offset0:42 offset1:44
	ds_write_b32 v1, v4 offset:11776
	s_waitcnt lgkmcnt(0)
	v_readfirstlane_b32 s98, v130
	v_readfirstlane_b32 s99, v131
	v_lshlrev_b32_e32 v92, 4, v176
	s_mov_b32 s95, 0
	s_cmp_lg_u64 s[0:1], 0
	s_cselect_b32 s34, 0, 31
	s_lshl_b32 s36, s34, 4
	v_add_u32_e32 v89, s36, v181
	s_add_i32 s10, s93, s36
	v_mov_b32_e32 v91, s10
	s_mov_b32 s12, s98
	s_and_b32 s13, s99, 0xffff
	s_or_b32 s13, s13, 0x4000000
	s_mov_b32 s14, -1
	s_mov_b32 s15, 0x20000
	v_mov_b32_e32 v67, v92
	v_mov_b32_e32 v69, v92
	v_mov_b32_e32 v71, v92
	v_mov_b32_e32 v73, v92
	v_mov_b32_e32 v75, v92
	v_mov_b32_e32 v77, v92
	v_mov_b32_e32 v79, v92
	v_mov_b32_e32 v81, v92
	v_mov_b32_e32 v237, v92
	v_mov_b32_e32 v239, v92
	v_mov_b32_e32 v241, v92
	v_mov_b32_e32 v243, v92
	v_mov_b32_e32 v245, v92
	v_mov_b32_e32 v247, v92
	v_mov_b32_e32 v253, v92
	v_mov_b32_e32 v145, v92
	ds_read_b32 v66, v91 offset:0
	ds_read_b32 v68, v91 offset:4
	ds_read_b32 v70, v91 offset:8
	ds_read_b32 v72, v91 offset:12
	ds_read_b32 v74, v91 offset:1536
	ds_read_b32 v76, v91 offset:1540
	ds_read_b32 v78, v91 offset:1544
	ds_read_b32 v80, v91 offset:1548
	ds_read_b32 v236, v91 offset:3072
	ds_read_b32 v238, v91 offset:3076
	ds_read_b32 v240, v91 offset:3080
	ds_read_b32 v242, v91 offset:3084
	ds_read_b32 v244, v91 offset:4608
	ds_read_b32 v246, v91 offset:4612
	ds_read_b32 v252, v91 offset:4616
	ds_read_b32 v144, v91 offset:4620
	s_waitcnt lgkmcnt(12)
	buffer_load_dwordx4 v[2:5], v[66:67], s[12:15], 0 idxen offen
	buffer_load_dwordx4 v[6:9], v[68:69], s[12:15], 0 idxen offen
	buffer_load_dwordx4 v[10:13], v[70:71], s[12:15], 0 idxen offen
	buffer_load_dwordx4 v[14:17], v[72:73], s[12:15], 0 idxen offen
	ds_read_b32 v82, v89 offset:1024
	s_waitcnt lgkmcnt(9)
	buffer_load_dwordx4 v[18:21], v[74:75], s[12:15], 0 idxen offen
	buffer_load_dwordx4 v[22:25], v[76:77], s[12:15], 0 idxen offen
	buffer_load_dwordx4 v[26:29], v[78:79], s[12:15], 0 idxen offen
	buffer_load_dwordx4 v[30:33], v[80:81], s[12:15], 0 idxen offen
	ds_read_b32 v83, v89 offset:2560
	s_waitcnt lgkmcnt(6)
	buffer_load_dwordx4 v[34:37], v[236:237], s[12:15], 0 idxen offen
	buffer_load_dwordx4 v[38:41], v[238:239], s[12:15], 0 idxen offen
	buffer_load_dwordx4 v[42:45], v[240:241], s[12:15], 0 idxen offen
	buffer_load_dwordx4 v[46:49], v[242:243], s[12:15], 0 idxen offen
	ds_read_b32 v84, v89 offset:4096
	s_waitcnt lgkmcnt(3)
	buffer_load_dwordx4 v[50:53], v[244:245], s[12:15], 0 idxen offen
	buffer_load_dwordx4 v[54:57], v[246:247], s[12:15], 0 idxen offen
	buffer_load_dwordx4 v[58:61], v[252:253], s[12:15], 0 idxen offen
	buffer_load_dwordx4 v[62:65], v[144:145], s[12:15], 0 idxen offen
	ds_read_b32 v85, v89 offset:5632
	ds_read_b32 v66, v91 offset:6144
	ds_read_b32 v68, v91 offset:6148
	ds_read_b32 v70, v91 offset:6152
	ds_read_b32 v72, v91 offset:6156
	ds_read_b32 v74, v91 offset:7680
	ds_read_b32 v76, v91 offset:7684
	ds_read_b32 v78, v91 offset:7688
	ds_read_b32 v80, v91 offset:7692
	ds_read_b32 v236, v91 offset:9216
	ds_read_b32 v238, v91 offset:9220
	ds_read_b32 v240, v91 offset:9224
	ds_read_b32 v242, v91 offset:9228
	ds_read_b32 v244, v91 offset:10752
	ds_read_b32 v246, v91 offset:10756
	ds_read_b32 v252, v91 offset:10760
	ds_read_b32 v144, v91 offset:10764
	s_add_i32 s10, s34, 1
	s_min_u32 s10, s10, 31
	s_sub_i32 s11, s34, 1
	s_max_i32 s11, s11, 0
	s_cmp_lg_u64 s[0:1], 0
	s_cselect_b32 s35, s10, s11
	s_lshl_b32 s36, s35, 4
	v_add_u32_e32 v90, s36, v181
	s_add_i32 s10, s93, s36
	s_waitcnt vmcnt(12) lgkmcnt(0)
	v_mov_b32_e32 v91, s10
	v_mul_f32_e32 v88, v141, v82
	v_mfma_f32_16x16x32_fp8_fp8 v[184:187], v[2:3], v[122:123], 0
	v_mfma_f32_16x16x32_fp8_fp8 v[188:191], v[6:7], v[122:123], 0
	v_mfma_f32_16x16x32_fp8_fp8 v[192:195], v[10:11], v[122:123], 0
	v_mfma_f32_16x16x32_fp8_fp8 v[196:199], v[14:15], v[122:123], 0
	v_mfma_f32_16x16x32_fp8_fp8 v[184:187], v[4:5], v[124:125], v[184:187]
	v_mfma_f32_16x16x32_fp8_fp8 v[188:191], v[8:9], v[124:125], v[188:191]
	v_mfma_f32_16x16x32_fp8_fp8 v[192:195], v[12:13], v[124:125], v[192:195]
	v_mfma_f32_16x16x32_fp8_fp8 v[196:199], v[16:17], v[124:125], v[196:199]
	buffer_load_dwordx4 v[2:5], v[66:67], s[12:15], 0 idxen offen
	buffer_load_dwordx4 v[6:9], v[68:69], s[12:15], 0 idxen offen
	buffer_load_dwordx4 v[10:13], v[70:71], s[12:15], 0 idxen offen
	buffer_load_dwordx4 v[14:17], v[72:73], s[12:15], 0 idxen offen
	ds_read_b32 v82, v89 offset:7168
	ds_read_b32 v66, v91 offset:0
	ds_read_b32 v68, v91 offset:4
	ds_read_b32 v70, v91 offset:8
	ds_read_b32 v72, v91 offset:12
.Lus_loop:
	s_barrier
	s_waitcnt vmcnt(12) lgkmcnt(15)
	v_mul_f32_e32 v1, v140, v83
	v_add_f32_dpp v184, v185, v184 quad_perm:[1,1,1,1] row_mask:0xf bank_mask:0xf bound_ctrl:1
	v_add_f32_dpp v186, v187, v186 quad_perm:[3,3,3,3] row_mask:0xf bank_mask:0xf bound_ctrl:1
	v_mfma_f32_16x16x32_fp8_fp8 v[200:203], v[18:19], v[118:119], 0
	v_add_f32_dpp v189, v188, v189 quad_perm:[0,0,0,0] row_mask:0xf bank_mask:0xf bound_ctrl:1
	v_add_f32_dpp v190, v191, v190 quad_perm:[3,3,3,3] row_mask:0xf bank_mask:0xf bound_ctrl:1
	v_mfma_f32_16x16x32_fp8_fp8 v[204:207], v[22:23], v[118:119], 0
	v_add_f32_dpp v194, v195, v194 quad_perm:[3,3,3,3] row_mask:0xf bank_mask:0xf bound_ctrl:1
	v_add_f32_dpp v192, v193, v192 quad_perm:[1,1,1,1] row_mask:0xf bank_mask:0xf bound_ctrl:1
	v_mfma_f32_16x16x32_fp8_fp8 v[228:231], v[26:27], v[118:119], 0
	v_add_f32_dpp v199, v198, v199 quad_perm:[2,2,2,2] row_mask:0xf bank_mask:0xf bound_ctrl:1
	v_add_f32_dpp v196, v197, v196 quad_perm:[1,1,1,1] row_mask:0xf bank_mask:0xf bound_ctrl:1
	v_mfma_f32_16x16x32_fp8_fp8 v[232:235], v[30:31], v[118:119], 0
	v_add_f32_dpp v184, v186, v184 quad_perm:[2,2,2,2] row_mask:0xf bank_mask:0xf bound_ctrl:1
	v_add_f32_dpp v189, v190, v189 quad_perm:[2,2,2,2] row_mask:0xf bank_mask:0xf bound_ctrl:1
	v_mfma_f32_16x16x32_fp8_fp8 v[200:203], v[20:21], v[120:121], v[200:203]
	v_add_f32_dpp v194, v192, v194 quad_perm:[0,0,0,0] row_mask:0xf bank_mask:0xf bound_ctrl:1
	v_add_f32_dpp v199, v196, v199 quad_perm:[0,0,0,0] row_mask:0xf bank_mask:0xf bound_ctrl:1
	v_mfma_f32_16x16x32_fp8_fp8 v[204:207], v[24:25], v[120:121], v[204:207]
	v_cndmask_b32_e64 v146, v189, v184, s[2:3]
	v_cndmask_b32_e64 v142, v199, v194, s[2:3]
	v_mfma_f32_16x16x32_fp8_fp8 v[228:231], v[28:29], v[120:121], v[228:231]
	v_cndmask_b32_e64 v86, v142, v146, s[4:5]
	v_mfma_f32_16x16x32_fp8_fp8 v[232:235], v[32:33], v[120:121], v[232:235]
	v_cndmask_b32_e64 v86, 0, v86, s[6:7]
	buffer_load_dwordx4 v[18:21], v[74:75], s[12:15], 0 idxen offen
	buffer_load_dwordx4 v[22:25], v[76:77], s[12:15], 0 idxen offen
	v_add_f32_dpp v86, v86, v86 row_ror:4 row_mask:0xf bank_mask:0xf bound_ctrl:1
	buffer_load_dwordx4 v[26:29], v[78:79], s[12:15], 0 idxen offen
	buffer_load_dwordx4 v[30:33], v[80:81], s[12:15], 0 idxen offen
	v_add_f32_dpp v86, v86, v86 row_ror:8 row_mask:0xf bank_mask:0xf bound_ctrl:1
	v_mov_b32_e32 v87, v86
	ds_read_b32 v83, v89 offset:8704
	ds_read_b32 v74, v91 offset:1536
	v_permlane16_swap_b32_e32 v86, v87
	v_add_f32_e32 v86, v86, v87
	v_mov_b32_e32 v87, v86
	ds_read_b32 v76, v91 offset:1540
	ds_read_b32 v78, v91 offset:1544
	ds_read_b32 v80, v91 offset:1548
	v_permlane32_swap_b32 v86, v87
	v_add_f32_e32 v86, v86, v87
	v_mul_f32_e32 v93, v88, v86
	s_mov_b64 exec, s[8:9]
	ds_write_b32 v89, v93 offset:1024
	s_mov_b64 exec, -1
	s_waitcnt vmcnt(12) lgkmcnt(15)
	v_mul_f32_e32 v88, v139, v84
	v_add_f32_dpp v200, v201, v200 quad_perm:[1,1,1,1] row_mask:0xf bank_mask:0xf bound_ctrl:1
	v_add_f32_dpp v202, v203, v202 quad_perm:[3,3,3,3] row_mask:0xf bank_mask:0xf bound_ctrl:1
	v_mfma_f32_16x16x32_fp8_fp8 v[184:187], v[34:35], v[114:115], 0
	v_add_f32_dpp v205, v204, v205 quad_perm:[0,0,0,0] row_mask:0xf bank_mask:0xf bound_ctrl:1
	v_add_f32_dpp v206, v207, v206 quad_perm:[3,3,3,3] row_mask:0xf bank_mask:0xf bound_ctrl:1
	v_mfma_f32_16x16x32_fp8_fp8 v[188:191], v[38:39], v[114:115], 0
	v_add_f32_dpp v230, v231, v230 quad_perm:[3,3,3,3] row_mask:0xf bank_mask:0xf bound_ctrl:1
	v_add_f32_dpp v228, v229, v228 quad_perm:[1,1,1,1] row_mask:0xf bank_mask:0xf bound_ctrl:1
	v_mfma_f32_16x16x32_fp8_fp8 v[192:195], v[42:43], v[114:115], 0
	v_add_f32_dpp v235, v234, v235 quad_perm:[2,2,2,2] row_mask:0xf bank_mask:0xf bound_ctrl:1
	v_add_f32_dpp v232, v233, v232 quad_perm:[1,1,1,1] row_mask:0xf bank_mask:0xf bound_ctrl:1
	v_mfma_f32_16x16x32_fp8_fp8 v[196:199], v[46:47], v[114:115], 0
	v_add_f32_dpp v200, v202, v200 quad_perm:[2,2,2,2] row_mask:0xf bank_mask:0xf bound_ctrl:1
	v_add_f32_dpp v205, v206, v205 quad_perm:[2,2,2,2] row_mask:0xf bank_mask:0xf bound_ctrl:1
	v_mfma_f32_16x16x32_fp8_fp8 v[184:187], v[36:37], v[116:117], v[184:187]
	v_add_f32_dpp v230, v228, v230 quad_perm:[0,0,0,0] row_mask:0xf bank_mask:0xf bound_ctrl:1
	v_add_f32_dpp v235, v232, v235 quad_perm:[0,0,0,0] row_mask:0xf bank_mask:0xf bound_ctrl:1
	v_mfma_f32_16x16x32_fp8_fp8 v[188:191], v[40:41], v[116:117], v[188:191]
	v_cndmask_b32_e64 v146, v205, v200, s[2:3]
	v_cndmask_b32_e64 v142, v235, v230, s[2:3]
	v_mfma_f32_16x16x32_fp8_fp8 v[192:195], v[44:45], v[116:117], v[192:195]
	v_cndmask_b32_e64 v86, v142, v146, s[4:5]
	v_mfma_f32_16x16x32_fp8_fp8 v[196:199], v[48:49], v[116:117], v[196:199]
	v_cndmask_b32_e64 v86, 0, v86, s[6:7]
	buffer_load_dwordx4 v[34:37], v[236:237], s[12:15], 0 idxen offen
	buffer_load_dwordx4 v[38:41], v[238:239], s[12:15], 0 idxen offen
	v_add_f32_dpp v86, v86, v86 row_ror:4 row_mask:0xf bank_mask:0xf bound_ctrl:1
	buffer_load_dwordx4 v[42:45], v[240:241], s[12:15], 0 idxen offen
	buffer_load_dwordx4 v[46:49], v[242:243], s[12:15], 0 idxen offen
	v_add_f32_dpp v86, v86, v86 row_ror:8 row_mask:0xf bank_mask:0xf bound_ctrl:1
	v_mov_b32_e32 v87, v86
	ds_read_b32 v84, v89 offset:10240
	ds_read_b32 v236, v91 offset:3072
	v_permlane16_swap_b32_e32 v86, v87
	v_add_f32_e32 v86, v86, v87
	v_mov_b32_e32 v87, v86
	ds_read_b32 v238, v91 offset:3076
	ds_read_b32 v240, v91 offset:3080
	ds_read_b32 v242, v91 offset:3084
	v_permlane32_swap_b32 v86, v87
	v_add_f32_e32 v86, v86, v87
	v_mul_f32_e32 v93, v1, v86
	s_mov_b64 exec, s[8:9]
	ds_write_b32 v89, v93 offset:2560
	s_mov_b64 exec, -1
	s_waitcnt vmcnt(12) lgkmcnt(15)
	v_mul_f32_e32 v1, v138, v85
	v_add_f32_dpp v184, v185, v184 quad_perm:[1,1,1,1] row_mask:0xf bank_mask:0xf bound_ctrl:1
	v_add_f32_dpp v186, v187, v186 quad_perm:[3,3,3,3] row_mask:0xf bank_mask:0xf bound_ctrl:1
	v_mfma_f32_16x16x32_fp8_fp8 v[200:203], v[50:51], v[110:111], 0
	v_add_f32_dpp v189, v188, v189 quad_perm:[0,0,0,0] row_mask:0xf bank_mask:0xf bound_ctrl:1
	v_add_f32_dpp v190, v191, v190 quad_perm:[3,3,3,3] row_mask:0xf bank_mask:0xf bound_ctrl:1
	v_mfma_f32_16x16x32_fp8_fp8 v[204:207], v[54:55], v[110:111], 0
	v_add_f32_dpp v194, v195, v194 quad_perm:[3,3,3,3] row_mask:0xf bank_mask:0xf bound_ctrl:1
	v_add_f32_dpp v192, v193, v192 quad_perm:[1,1,1,1] row_mask:0xf bank_mask:0xf bound_ctrl:1
	v_mfma_f32_16x16x32_fp8_fp8 v[228:231], v[58:59], v[110:111], 0
	v_add_f32_dpp v199, v198, v199 quad_perm:[2,2,2,2] row_mask:0xf bank_mask:0xf bound_ctrl:1
	v_add_f32_dpp v196, v197, v196 quad_perm:[1,1,1,1] row_mask:0xf bank_mask:0xf bound_ctrl:1
	v_mfma_f32_16x16x32_fp8_fp8 v[232:235], v[62:63], v[110:111], 0
	v_add_f32_dpp v184, v186, v184 quad_perm:[2,2,2,2] row_mask:0xf bank_mask:0xf bound_ctrl:1
	v_add_f32_dpp v189, v190, v189 quad_perm:[2,2,2,2] row_mask:0xf bank_mask:0xf bound_ctrl:1
	v_mfma_f32_16x16x32_fp8_fp8 v[200:203], v[52:53], v[112:113], v[200:203]
	v_add_f32_dpp v194, v192, v194 quad_perm:[0,0,0,0] row_mask:0xf bank_mask:0xf bound_ctrl:1
	v_add_f32_dpp v199, v196, v199 quad_perm:[0,0,0,0] row_mask:0xf bank_mask:0xf bound_ctrl:1
	v_mfma_f32_16x16x32_fp8_fp8 v[204:207], v[56:57], v[112:113], v[204:207]
	v_cndmask_b32_e64 v146, v189, v184, s[2:3]
	v_cndmask_b32_e64 v142, v199, v194, s[2:3]
	v_mfma_f32_16x16x32_fp8_fp8 v[228:231], v[60:61], v[112:113], v[228:231]
	v_cndmask_b32_e64 v86, v142, v146, s[4:5]
	v_mfma_f32_16x16x32_fp8_fp8 v[232:235], v[64:65], v[112:113], v[232:235]
	v_cndmask_b32_e64 v86, 0, v86, s[6:7]
	buffer_load_dwordx4 v[50:53], v[244:245], s[12:15], 0 idxen offen
	buffer_load_dwordx4 v[54:57], v[246:247], s[12:15], 0 idxen offen
	v_add_f32_dpp v86, v86, v86 row_ror:4 row_mask:0xf bank_mask:0xf bound_ctrl:1
	buffer_load_dwordx4 v[58:61], v[252:253], s[12:15], 0 idxen offen
	buffer_load_dwordx4 v[62:65], v[144:145], s[12:15], 0 idxen offen
	v_add_f32_dpp v86, v86, v86 row_ror:8 row_mask:0xf bank_mask:0xf bound_ctrl:1
	v_mov_b32_e32 v87, v86
	ds_read_b32 v85, v89 offset:11776
	ds_read_b32 v244, v91 offset:4608
	v_permlane16_swap_b32_e32 v86, v87
	v_add_f32_e32 v86, v86, v87
	v_mov_b32_e32 v87, v86
	ds_read_b32 v246, v91 offset:4612
	ds_read_b32 v252, v91 offset:4616
	ds_read_b32 v144, v91 offset:4620
	v_permlane32_swap_b32 v86, v87
	v_add_f32_e32 v86, v86, v87
	v_mul_f32_e32 v93, v88, v86
	s_mov_b64 exec, s[8:9]
	ds_write_b32 v89, v93 offset:4096
	s_mov_b64 exec, -1
	s_waitcnt vmcnt(12) lgkmcnt(15)
	v_mul_f32_e32 v88, v137, v82
	v_add_f32_dpp v200, v201, v200 quad_perm:[1,1,1,1] row_mask:0xf bank_mask:0xf bound_ctrl:1
	v_add_f32_dpp v202, v203, v202 quad_perm:[3,3,3,3] row_mask:0xf bank_mask:0xf bound_ctrl:1
	v_mfma_f32_16x16x32_fp8_fp8 v[184:187], v[2:3], v[106:107], 0
	v_add_f32_dpp v205, v204, v205 quad_perm:[0,0,0,0] row_mask:0xf bank_mask:0xf bound_ctrl:1
	v_add_f32_dpp v206, v207, v206 quad_perm:[3,3,3,3] row_mask:0xf bank_mask:0xf bound_ctrl:1
	v_mfma_f32_16x16x32_fp8_fp8 v[188:191], v[6:7], v[106:107], 0
	v_add_f32_dpp v230, v231, v230 quad_perm:[3,3,3,3] row_mask:0xf bank_mask:0xf bound_ctrl:1
	v_add_f32_dpp v228, v229, v228 quad_perm:[1,1,1,1] row_mask:0xf bank_mask:0xf bound_ctrl:1
	v_mfma_f32_16x16x32_fp8_fp8 v[192:195], v[10:11], v[106:107], 0
	v_add_f32_dpp v235, v234, v235 quad_perm:[2,2,2,2] row_mask:0xf bank_mask:0xf bound_ctrl:1
	v_add_f32_dpp v232, v233, v232 quad_perm:[1,1,1,1] row_mask:0xf bank_mask:0xf bound_ctrl:1
	v_mfma_f32_16x16x32_fp8_fp8 v[196:199], v[14:15], v[106:107], 0
	v_add_f32_dpp v200, v202, v200 quad_perm:[2,2,2,2] row_mask:0xf bank_mask:0xf bound_ctrl:1
	v_add_f32_dpp v205, v206, v205 quad_perm:[2,2,2,2] row_mask:0xf bank_mask:0xf bound_ctrl:1
	v_mfma_f32_16x16x32_fp8_fp8 v[184:187], v[4:5], v[108:109], v[184:187]
	v_add_f32_dpp v230, v228, v230 quad_perm:[0,0,0,0] row_mask:0xf bank_mask:0xf bound_ctrl:1
	v_add_f32_dpp v235, v232, v235 quad_perm:[0,0,0,0] row_mask:0xf bank_mask:0xf bound_ctrl:1
	v_mfma_f32_16x16x32_fp8_fp8 v[188:191], v[8:9], v[108:109], v[188:191]
	v_cndmask_b32_e64 v146, v205, v200, s[2:3]
	v_cndmask_b32_e64 v142, v235, v230, s[2:3]
	v_mfma_f32_16x16x32_fp8_fp8 v[192:195], v[12:13], v[108:109], v[192:195]
	v_cndmask_b32_e64 v86, v142, v146, s[4:5]
	v_mfma_f32_16x16x32_fp8_fp8 v[196:199], v[16:17], v[108:109], v[196:199]
	v_cndmask_b32_e64 v86, 0, v86, s[6:7]
	buffer_load_dwordx4 v[2:5], v[66:67], s[12:15], 0 idxen offen
	buffer_load_dwordx4 v[6:9], v[68:69], s[12:15], 0 idxen offen
	v_add_f32_dpp v86, v86, v86 row_ror:4 row_mask:0xf bank_mask:0xf bound_ctrl:1
	buffer_load_dwordx4 v[10:13], v[70:71], s[12:15], 0 idxen offen
	buffer_load_dwordx4 v[14:17], v[72:73], s[12:15], 0 idxen offen
	v_add_f32_dpp v86, v86, v86 row_ror:8 row_mask:0xf bank_mask:0xf bound_ctrl:1
	v_mov_b32_e32 v87, v86
	ds_read_b32 v82, v90 offset:1024
	ds_read_b32 v66, v91 offset:6144
	v_permlane16_swap_b32_e32 v86, v87
	v_add_f32_e32 v86, v86, v87
	v_mov_b32_e32 v87, v86
	ds_read_b32 v68, v91 offset:6148
	ds_read_b32 v70, v91 offset:6152
	ds_read_b32 v72, v91 offset:6156
	v_permlane32_swap_b32 v86, v87
	v_add_f32_e32 v86, v86, v87
	v_mul_f32_e32 v93, v1, v86
	s_mov_b64 exec, s[8:9]
	ds_write_b32 v89, v93 offset:5632
	s_mov_b64 exec, -1
	s_waitcnt vmcnt(12) lgkmcnt(15)
	v_mul_f32_e32 v1, v136, v83
	v_add_f32_dpp v184, v185, v184 quad_perm:[1,1,1,1] row_mask:0xf bank_mask:0xf bound_ctrl:1
	v_add_f32_dpp v186, v187, v186 quad_perm:[3,3,3,3] row_mask:0xf bank_mask:0xf bound_ctrl:1
	v_mfma_f32_16x16x32_fp8_fp8 v[200:203], v[18:19], v[102:103], 0
	v_add_f32_dpp v189, v188, v189 quad_perm:[0,0,0,0] row_mask:0xf bank_mask:0xf bound_ctrl:1
	v_add_f32_dpp v190, v191, v190 quad_perm:[3,3,3,3] row_mask:0xf bank_mask:0xf bound_ctrl:1
	v_mfma_f32_16x16x32_fp8_fp8 v[204:207], v[22:23], v[102:103], 0
	v_add_f32_dpp v194, v195, v194 quad_perm:[3,3,3,3] row_mask:0xf bank_mask:0xf bound_ctrl:1
	v_add_f32_dpp v192, v193, v192 quad_perm:[1,1,1,1] row_mask:0xf bank_mask:0xf bound_ctrl:1
	v_mfma_f32_16x16x32_fp8_fp8 v[228:231], v[26:27], v[102:103], 0
	v_add_f32_dpp v199, v198, v199 quad_perm:[2,2,2,2] row_mask:0xf bank_mask:0xf bound_ctrl:1
	v_add_f32_dpp v196, v197, v196 quad_perm:[1,1,1,1] row_mask:0xf bank_mask:0xf bound_ctrl:1
	v_mfma_f32_16x16x32_fp8_fp8 v[232:235], v[30:31], v[102:103], 0
	v_add_f32_dpp v184, v186, v184 quad_perm:[2,2,2,2] row_mask:0xf bank_mask:0xf bound_ctrl:1
	v_add_f32_dpp v189, v190, v189 quad_perm:[2,2,2,2] row_mask:0xf bank_mask:0xf bound_ctrl:1
	v_mfma_f32_16x16x32_fp8_fp8 v[200:203], v[20:21], v[104:105], v[200:203]
	v_add_f32_dpp v194, v192, v194 quad_perm:[0,0,0,0] row_mask:0xf bank_mask:0xf bound_ctrl:1
	v_add_f32_dpp v199, v196, v199 quad_perm:[0,0,0,0] row_mask:0xf bank_mask:0xf bound_ctrl:1
	v_mfma_f32_16x16x32_fp8_fp8 v[204:207], v[24:25], v[104:105], v[204:207]
	v_cndmask_b32_e64 v146, v189, v184, s[2:3]
	v_cndmask_b32_e64 v142, v199, v194, s[2:3]
	v_mfma_f32_16x16x32_fp8_fp8 v[228:231], v[28:29], v[104:105], v[228:231]
	v_cndmask_b32_e64 v86, v142, v146, s[4:5]
	v_mfma_f32_16x16x32_fp8_fp8 v[232:235], v[32:33], v[104:105], v[232:235]
	v_cndmask_b32_e64 v86, 0, v86, s[6:7]
	buffer_load_dwordx4 v[18:21], v[74:75], s[12:15], 0 idxen offen
	buffer_load_dwordx4 v[22:25], v[76:77], s[12:15], 0 idxen offen
	v_add_f32_dpp v86, v86, v86 row_ror:4 row_mask:0xf bank_mask:0xf bound_ctrl:1
	buffer_load_dwordx4 v[26:29], v[78:79], s[12:15], 0 idxen offen
	buffer_load_dwordx4 v[30:33], v[80:81], s[12:15], 0 idxen offen
	v_add_f32_dpp v86, v86, v86 row_ror:8 row_mask:0xf bank_mask:0xf bound_ctrl:1
	v_mov_b32_e32 v87, v86
	ds_read_b32 v83, v90 offset:2560
	ds_read_b32 v74, v91 offset:7680
	v_permlane16_swap_b32_e32 v86, v87
	v_add_f32_e32 v86, v86, v87
	v_mov_b32_e32 v87, v86
	ds_read_b32 v76, v91 offset:7684
	ds_read_b32 v78, v91 offset:7688
	ds_read_b32 v80, v91 offset:7692
	v_permlane32_swap_b32 v86, v87
	v_add_f32_e32 v86, v86, v87
	v_mul_f32_e32 v93, v88, v86
	s_mov_b64 exec, s[8:9]
	ds_write_b32 v89, v93 offset:7168
	s_mov_b64 exec, -1
	s_waitcnt vmcnt(12) lgkmcnt(15)
	v_mul_f32_e32 v88, v129, v84
	v_add_f32_dpp v200, v201, v200 quad_perm:[1,1,1,1] row_mask:0xf bank_mask:0xf bound_ctrl:1
	v_add_f32_dpp v202, v203, v202 quad_perm:[3,3,3,3] row_mask:0xf bank_mask:0xf bound_ctrl:1
	v_mfma_f32_16x16x32_fp8_fp8 v[184:187], v[34:35], v[98:99], 0
	v_add_f32_dpp v205, v204, v205 quad_perm:[0,0,0,0] row_mask:0xf bank_mask:0xf bound_ctrl:1
	v_add_f32_dpp v206, v207, v206 quad_perm:[3,3,3,3] row_mask:0xf bank_mask:0xf bound_ctrl:1
	v_mfma_f32_16x16x32_fp8_fp8 v[188:191], v[38:39], v[98:99], 0
	v_add_f32_dpp v230, v231, v230 quad_perm:[3,3,3,3] row_mask:0xf bank_mask:0xf bound_ctrl:1
	v_add_f32_dpp v228, v229, v228 quad_perm:[1,1,1,1] row_mask:0xf bank_mask:0xf bound_ctrl:1
	v_mfma_f32_16x16x32_fp8_fp8 v[192:195], v[42:43], v[98:99], 0
	v_add_f32_dpp v235, v234, v235 quad_perm:[2,2,2,2] row_mask:0xf bank_mask:0xf bound_ctrl:1
	v_add_f32_dpp v232, v233, v232 quad_perm:[1,1,1,1] row_mask:0xf bank_mask:0xf bound_ctrl:1
	v_mfma_f32_16x16x32_fp8_fp8 v[196:199], v[46:47], v[98:99], 0
	v_add_f32_dpp v200, v202, v200 quad_perm:[2,2,2,2] row_mask:0xf bank_mask:0xf bound_ctrl:1
	v_add_f32_dpp v205, v206, v205 quad_perm:[2,2,2,2] row_mask:0xf bank_mask:0xf bound_ctrl:1
	v_mfma_f32_16x16x32_fp8_fp8 v[184:187], v[36:37], v[100:101], v[184:187]
	v_add_f32_dpp v230, v228, v230 quad_perm:[0,0,0,0] row_mask:0xf bank_mask:0xf bound_ctrl:1
	v_add_f32_dpp v235, v232, v235 quad_perm:[0,0,0,0] row_mask:0xf bank_mask:0xf bound_ctrl:1
	v_mfma_f32_16x16x32_fp8_fp8 v[188:191], v[40:41], v[100:101], v[188:191]
	v_cndmask_b32_e64 v146, v205, v200, s[2:3]
	v_cndmask_b32_e64 v142, v235, v230, s[2:3]
	v_mfma_f32_16x16x32_fp8_fp8 v[192:195], v[44:45], v[100:101], v[192:195]
	v_cndmask_b32_e64 v86, v142, v146, s[4:5]
	v_mfma_f32_16x16x32_fp8_fp8 v[196:199], v[48:49], v[100:101], v[196:199]
	v_cndmask_b32_e64 v86, 0, v86, s[6:7]
	buffer_load_dwordx4 v[34:37], v[236:237], s[12:15], 0 idxen offen
	buffer_load_dwordx4 v[38:41], v[238:239], s[12:15], 0 idxen offen
	v_add_f32_dpp v86, v86, v86 row_ror:4 row_mask:0xf bank_mask:0xf bound_ctrl:1
	buffer_load_dwordx4 v[42:45], v[240:241], s[12:15], 0 idxen offen
	buffer_load_dwordx4 v[46:49], v[242:243], s[12:15], 0 idxen offen
	v_add_f32_dpp v86, v86, v86 row_ror:8 row_mask:0xf bank_mask:0xf bound_ctrl:1
	v_mov_b32_e32 v87, v86
	ds_read_b32 v84, v90 offset:4096
	ds_read_b32 v236, v91 offset:9216
	v_permlane16_swap_b32_e32 v86, v87
	v_add_f32_e32 v86, v86, v87
	v_mov_b32_e32 v87, v86
	ds_read_b32 v238, v91 offset:9220
	ds_read_b32 v240, v91 offset:9224
	ds_read_b32 v242, v91 offset:9228
	v_permlane32_swap_b32 v86, v87
	v_add_f32_e32 v86, v86, v87
	v_mul_f32_e32 v93, v1, v86
	s_mov_b64 exec, s[8:9]
	ds_write_b32 v89, v93 offset:8704
	s_mov_b64 exec, -1
	s_waitcnt vmcnt(12) lgkmcnt(15)
	v_mul_f32_e32 v1, v128, v85
	v_add_f32_dpp v184, v185, v184 quad_perm:[1,1,1,1] row_mask:0xf bank_mask:0xf bound_ctrl:1
	v_add_f32_dpp v186, v187, v186 quad_perm:[3,3,3,3] row_mask:0xf bank_mask:0xf bound_ctrl:1
	v_mfma_f32_16x16x32_fp8_fp8 v[200:203], v[50:51], v[94:95], 0
	v_add_f32_dpp v189, v188, v189 quad_perm:[0,0,0,0] row_mask:0xf bank_mask:0xf bound_ctrl:1
	v_add_f32_dpp v190, v191, v190 quad_perm:[3,3,3,3] row_mask:0xf bank_mask:0xf bound_ctrl:1
	v_mfma_f32_16x16x32_fp8_fp8 v[204:207], v[54:55], v[94:95], 0
	v_add_f32_dpp v194, v195, v194 quad_perm:[3,3,3,3] row_mask:0xf bank_mask:0xf bound_ctrl:1
	v_add_f32_dpp v192, v193, v192 quad_perm:[1,1,1,1] row_mask:0xf bank_mask:0xf bound_ctrl:1
	v_mfma_f32_16x16x32_fp8_fp8 v[228:231], v[58:59], v[94:95], 0
	v_add_f32_dpp v199, v198, v199 quad_perm:[2,2,2,2] row_mask:0xf bank_mask:0xf bound_ctrl:1
	v_add_f32_dpp v196, v197, v196 quad_perm:[1,1,1,1] row_mask:0xf bank_mask:0xf bound_ctrl:1
	v_mfma_f32_16x16x32_fp8_fp8 v[232:235], v[62:63], v[94:95], 0
	v_add_f32_dpp v184, v186, v184 quad_perm:[2,2,2,2] row_mask:0xf bank_mask:0xf bound_ctrl:1
	v_add_f32_dpp v189, v190, v189 quad_perm:[2,2,2,2] row_mask:0xf bank_mask:0xf bound_ctrl:1
	v_mfma_f32_16x16x32_fp8_fp8 v[200:203], v[52:53], v[96:97], v[200:203]
	v_add_f32_dpp v194, v192, v194 quad_perm:[0,0,0,0] row_mask:0xf bank_mask:0xf bound_ctrl:1
	v_add_f32_dpp v199, v196, v199 quad_perm:[0,0,0,0] row_mask:0xf bank_mask:0xf bound_ctrl:1
	v_mfma_f32_16x16x32_fp8_fp8 v[204:207], v[56:57], v[96:97], v[204:207]
	v_cndmask_b32_e64 v146, v189, v184, s[2:3]
	v_cndmask_b32_e64 v142, v199, v194, s[2:3]
	v_mfma_f32_16x16x32_fp8_fp8 v[228:231], v[60:61], v[96:97], v[228:231]
	v_cndmask_b32_e64 v86, v142, v146, s[4:5]
	v_mfma_f32_16x16x32_fp8_fp8 v[232:235], v[64:65], v[96:97], v[232:235]
	v_cndmask_b32_e64 v86, 0, v86, s[6:7]
	buffer_load_dwordx4 v[50:53], v[244:245], s[12:15], 0 idxen offen
	buffer_load_dwordx4 v[54:57], v[246:247], s[12:15], 0 idxen offen
	v_add_f32_dpp v86, v86, v86 row_ror:4 row_mask:0xf bank_mask:0xf bound_ctrl:1
	buffer_load_dwordx4 v[58:61], v[252:253], s[12:15], 0 idxen offen
	buffer_load_dwordx4 v[62:65], v[144:145], s[12:15], 0 idxen offen
	v_add_f32_dpp v86, v86, v86 row_ror:8 row_mask:0xf bank_mask:0xf bound_ctrl:1
	v_mov_b32_e32 v87, v86
	ds_read_b32 v85, v90 offset:5632
	ds_read_b32 v244, v91 offset:10752
	v_permlane16_swap_b32_e32 v86, v87
	v_add_f32_e32 v86, v86, v87
	v_mov_b32_e32 v87, v86
	ds_read_b32 v246, v91 offset:10756
	ds_read_b32 v252, v91 offset:10760
	ds_read_b32 v144, v91 offset:10764
	v_permlane32_swap_b32 v86, v87
	v_add_f32_e32 v86, v86, v87
	v_mul_f32_e32 v93, v88, v86
	s_mov_b64 exec, s[8:9]
	ds_write_b32 v89, v93 offset:10240
	s_mov_b64 exec, -1
	s_waitcnt vmcnt(12) lgkmcnt(15)
	s_add_i32 s10, s35, 1
	s_min_u32 s10, s10, 31
	s_sub_i32 s11, s35, 1
	s_max_i32 s11, s11, 0
	s_cmp_lg_u64 s[0:1], 0
	s_cselect_b32 s72, s10, s11
	s_lshl_b32 s36, s72, 4
	s_add_i32 s10, s93, s36
	v_mov_b32_e32 v91, s10
	v_mul_f32_e32 v88, v141, v82
	v_add_f32_dpp v200, v201, v200 quad_perm:[1,1,1,1] row_mask:0xf bank_mask:0xf bound_ctrl:1
	v_add_f32_dpp v202, v203, v202 quad_perm:[3,3,3,3] row_mask:0xf bank_mask:0xf bound_ctrl:1
	v_mfma_f32_16x16x32_fp8_fp8 v[184:187], v[2:3], v[122:123], 0
	v_add_f32_dpp v205, v204, v205 quad_perm:[0,0,0,0] row_mask:0xf bank_mask:0xf bound_ctrl:1
	v_add_f32_dpp v206, v207, v206 quad_perm:[3,3,3,3] row_mask:0xf bank_mask:0xf bound_ctrl:1
	v_mfma_f32_16x16x32_fp8_fp8 v[188:191], v[6:7], v[122:123], 0
	v_add_f32_dpp v230, v231, v230 quad_perm:[3,3,3,3] row_mask:0xf bank_mask:0xf bound_ctrl:1
	v_add_f32_dpp v228, v229, v228 quad_perm:[1,1,1,1] row_mask:0xf bank_mask:0xf bound_ctrl:1
	v_mfma_f32_16x16x32_fp8_fp8 v[192:195], v[10:11], v[122:123], 0
	v_add_f32_dpp v235, v234, v235 quad_perm:[2,2,2,2] row_mask:0xf bank_mask:0xf bound_ctrl:1
	v_add_f32_dpp v232, v233, v232 quad_perm:[1,1,1,1] row_mask:0xf bank_mask:0xf bound_ctrl:1
	v_mfma_f32_16x16x32_fp8_fp8 v[196:199], v[14:15], v[122:123], 0
	v_add_f32_dpp v200, v202, v200 quad_perm:[2,2,2,2] row_mask:0xf bank_mask:0xf bound_ctrl:1
	v_add_f32_dpp v205, v206, v205 quad_perm:[2,2,2,2] row_mask:0xf bank_mask:0xf bound_ctrl:1
	v_mfma_f32_16x16x32_fp8_fp8 v[184:187], v[4:5], v[124:125], v[184:187]
	v_add_f32_dpp v230, v228, v230 quad_perm:[0,0,0,0] row_mask:0xf bank_mask:0xf bound_ctrl:1
	v_add_f32_dpp v235, v232, v235 quad_perm:[0,0,0,0] row_mask:0xf bank_mask:0xf bound_ctrl:1
	v_mfma_f32_16x16x32_fp8_fp8 v[188:191], v[8:9], v[124:125], v[188:191]
	v_cndmask_b32_e64 v146, v205, v200, s[2:3]
	v_cndmask_b32_e64 v142, v235, v230, s[2:3]
	v_mfma_f32_16x16x32_fp8_fp8 v[192:195], v[12:13], v[124:125], v[192:195]
	v_cndmask_b32_e64 v86, v142, v146, s[4:5]
	v_mfma_f32_16x16x32_fp8_fp8 v[196:199], v[16:17], v[124:125], v[196:199]
	v_cndmask_b32_e64 v86, 0, v86, s[6:7]
	buffer_load_dwordx4 v[2:5], v[66:67], s[12:15], 0 idxen offen
	buffer_load_dwordx4 v[6:9], v[68:69], s[12:15], 0 idxen offen
	v_add_f32_dpp v86, v86, v86 row_ror:4 row_mask:0xf bank_mask:0xf bound_ctrl:1
	buffer_load_dwordx4 v[10:13], v[70:71], s[12:15], 0 idxen offen
	buffer_load_dwordx4 v[14:17], v[72:73], s[12:15], 0 idxen offen
	v_add_f32_dpp v86, v86, v86 row_ror:8 row_mask:0xf bank_mask:0xf bound_ctrl:1
	v_mov_b32_e32 v87, v86
	ds_read_b32 v82, v90 offset:7168
	ds_read_b32 v66, v91 offset:0
	v_permlane16_swap_b32_e32 v86, v87
	v_add_f32_e32 v86, v86, v87
	v_mov_b32_e32 v87, v86
	ds_read_b32 v68, v91 offset:4
	ds_read_b32 v70, v91 offset:8
	ds_read_b32 v72, v91 offset:12
	v_permlane32_swap_b32 v86, v87
	v_add_f32_e32 v86, v86, v87
	v_mul_f32_e32 v93, v1, v86
	s_mov_b64 exec, s[8:9]
	ds_write_b32 v89, v93 offset:11776
	s_mov_b64 exec, -1
	v_mov_b32_e32 v89, v90
	v_add_u32_e32 v90, s36, v181
	s_mov_b32 s34, s35
	s_mov_b32 s35, s72
	s_add_i32 s95, s95, 1
	s_cmp_eq_u32 s95, 32
	s_cbranch_scc0 .Lus_loop
	s_waitcnt vmcnt(0) lgkmcnt(0)
	s_waitcnt lgkmcnt(0)
	s_waitcnt vmcnt(4)
	ds_read2st64_b32 v[2:3], v178 offset0:2 offset1:3
	ds_read2st64_b32 v[4:5], v178 offset0:4 offset1:5
	s_mov_b32 s0, 0x3e6d3388
	s_waitcnt lgkmcnt(0)
	v_fma_f32 v1, |v4|, s0, 1.0
	v_rcp_f32_e32 v1, v1
	v_cmp_gt_f32_e32 vcc, 0, v4
	v_fmamk_f32 v6, v1, 0x3f07dc22, v210
	v_fmaak_f32 v6, v1, v6, 0x3f35f0e3
	v_fmaak_f32 v6, v1, v6, 0xbe11a98e
	v_fmaak_f32 v6, v1, v6, 0x3e027906
	v_mul_f32_e32 v1, v1, v6
	v_mul_f32_e32 v6, v4, v4
	v_mul_f32_e32 v6, 0xbf38aa3b, v6
	v_exp_f32_e32 v6, v6
	s_nop 0
	v_mul_f32_e32 v1, v6, v1
	v_mul_f32_e32 v6, v4, v1
	v_fma_f32 v1, -v4, v1, v4
	v_cndmask_b32_e32 v1, v1, v6, vcc
	v_mul_f32_e32 v1, v2, v1
	v_fma_f32 v2, |v5|, s0, 1.0
	v_rcp_f32_e32 v2, v2
	v_cmp_gt_f32_e32 vcc, 0, v5
	v_fmamk_f32 v4, v2, 0x3f07dc22, v210
	v_fmaak_f32 v4, v2, v4, 0x3f35f0e3
	v_fmaak_f32 v4, v2, v4, 0xbe11a98e
	v_fmaak_f32 v4, v2, v4, 0x3e027906
	v_mul_f32_e32 v2, v2, v4
	v_mul_f32_e32 v4, v5, v5
	v_mul_f32_e32 v4, 0xbf38aa3b, v4
	v_exp_f32_e32 v4, v4
	s_nop 0
	v_mul_f32_e32 v2, v4, v2
	v_mul_f32_e32 v4, v5, v2
	v_fma_f32 v2, -v5, v2, v5
	v_cndmask_b32_e32 v2, v2, v4, vcc
	v_mul_f32_e32 v2, v3, v2
	v_max_f32_e64 v3, |v1|, |v2|
	s_nop 1
	v_mov_b32_dpp v4, v3 quad_perm:[1,0,3,2] row_mask:0xf bank_mask:0xf bound_ctrl:1
	v_max_f32_e32 v4, v4, v4
	v_max_f32_e32 v3, v3, v4
	s_nop 1
	v_mov_b32_dpp v4, v3 quad_perm:[2,3,0,1] row_mask:0xf bank_mask:0xf bound_ctrl:1
	v_max_f32_e32 v4, v4, v4
	v_max_f32_e32 v3, v3, v4
	s_nop 1
	v_mov_b32_dpp v4, v3 row_half_mirror row_mask:0xf bank_mask:0xf bound_ctrl:1
	v_max_f32_e32 v4, v4, v4
	v_max_f32_e32 v3, v3, v4
	s_nop 1
	v_mov_b32_dpp v4, v3 row_mirror row_mask:0xf bank_mask:0xf bound_ctrl:1
	v_max_f32_e32 v4, v4, v4
	v_max_f32_e32 v3, v3, v4
	s_nop 0
	v_readlane_b32 s0, v3, 0
	v_readlane_b32 s1, v3, 16
	v_readlane_b32 s10, v3, 32
	v_readlane_b32 s11, v3, 48
	v_max_f32_e64 v3, s1, s1
	v_max_f32_e64 v4, s0, s0
	v_max_f32_e32 v3, v4, v3
	v_max_f32_e64 v4, s11, s11
	v_max_f32_e64 v5, s10, s10
	v_max_f32_e32 v4, v5, v4
	s_mov_b32 s0, 0xda24260
	v_max3_f32 v3, v3, v4, s0
	s_mov_b64 s[0:1], exec
	v_readlane_b32 s10, v254, 21
	v_readlane_b32 s11, v254, 22
	s_and_b64 s[10:11], s[0:1], s[10:11]
	s_mov_b64 exec, s[10:11]
	v_mul_f32_e32 v4, 0x3b888889, v3
	v_mov_b32_e32 v5, s93
	ds_write_b32 v5, v4 offset:14336
	s_or_b64 exec, exec, s[0:1]
	s_mov_b32 s10, 0x43700000
	v_div_scale_f32 v4, s[0:1], v3, v3, s10
	v_rcp_f32_e32 v5, v4
	s_mov_b32 s0, 0x7020c0c
	v_fma_f32 v6, -v4, v5, 1.0
	v_fmac_f32_e32 v5, v6, v5
	v_div_scale_f32 v6, vcc, s10, v3, s10
	v_mul_f32_e32 v7, v6, v5
	v_fma_f32 v8, -v4, v7, v6
	v_fmac_f32_e32 v7, v8, v5
	v_fma_f32 v4, -v4, v7, v6
	v_div_fmas_f32 v4, v4, v5, v7
	v_div_fixup_f32 v3, v4, v3, s10
	v_mul_f32_e32 v4, v3, v1
	v_mul_f32_e32 v5, v3, v2
	v_mov_b32_e32 v6, v155
	v_cvt_pk_fp8_f32 v6, v4, v5
	v_cvt_pk_f32_fp8_e32 v[4:5], v6
	v_fma_f32 v1, v3, v1, -v4
	v_fma_f32 v2, v3, v2, -v5
	v_mov_b32_e32 v4, v155
	v_cvt_pk_fp8_f32 v4, v1, v2
	ds_read2st64_b32 v[2:3], v178 offset1:1
	v_lshlrev_b32_e32 v1, 16, v6
	v_and_b32_e32 v1, 0xff0000, v1
	v_lshlrev_b32_e32 v5, 24, v4
	v_lshlrev_b32_e32 v4, 16, v4
	s_waitcnt lgkmcnt(0)
	v_or3_b32 v1, v2, v1, v5
	v_lshlrev_b32_e32 v2, 8, v6
	v_perm_b32 v2, v4, v2, s0
	v_or_b32_e32 v2, v2, v3
	ds_write2st64_b32 v178, v1, v2 offset0:2 offset1:3
	ds_read2st64_b32 v[2:3], v178 offset0:8 offset1:9
	ds_read2st64_b32 v[4:5], v178 offset0:10 offset1:11
	s_mov_b32 s0, 0x3e6d3388
	s_waitcnt lgkmcnt(0)
	v_fma_f32 v1, |v4|, s0, 1.0
	v_rcp_f32_e32 v1, v1
	v_cmp_gt_f32_e32 vcc, 0, v4
	v_fmamk_f32 v6, v1, 0x3f07dc22, v210
	v_fmaak_f32 v6, v1, v6, 0x3f35f0e3
	v_fmaak_f32 v6, v1, v6, 0xbe11a98e
	v_fmaak_f32 v6, v1, v6, 0x3e027906
	v_mul_f32_e32 v1, v1, v6
	v_mul_f32_e32 v6, v4, v4
	v_mul_f32_e32 v6, 0xbf38aa3b, v6
	v_exp_f32_e32 v6, v6
	s_nop 0
	v_mul_f32_e32 v1, v6, v1
	v_mul_f32_e32 v6, v4, v1
	v_fma_f32 v1, -v4, v1, v4
	v_cndmask_b32_e32 v1, v1, v6, vcc
	v_mul_f32_e32 v1, v2, v1
	v_fma_f32 v2, |v5|, s0, 1.0
	v_rcp_f32_e32 v2, v2
	v_cmp_gt_f32_e32 vcc, 0, v5
	v_fmamk_f32 v4, v2, 0x3f07dc22, v210
	v_fmaak_f32 v4, v2, v4, 0x3f35f0e3
	v_fmaak_f32 v4, v2, v4, 0xbe11a98e
	v_fmaak_f32 v4, v2, v4, 0x3e027906
	v_mul_f32_e32 v2, v2, v4
	v_mul_f32_e32 v4, v5, v5
	v_mul_f32_e32 v4, 0xbf38aa3b, v4
	v_exp_f32_e32 v4, v4
	s_nop 0
	v_mul_f32_e32 v2, v4, v2
	v_mul_f32_e32 v4, v5, v2
	v_fma_f32 v2, -v5, v2, v5
	v_cndmask_b32_e32 v2, v2, v4, vcc
	v_mul_f32_e32 v2, v3, v2
	v_max_f32_e64 v3, |v1|, |v2|
	s_nop 1
	v_mov_b32_dpp v4, v3 quad_perm:[1,0,3,2] row_mask:0xf bank_mask:0xf bound_ctrl:1
	v_max_f32_e32 v4, v4, v4
	v_max_f32_e32 v3, v3, v4
	s_nop 1
	v_mov_b32_dpp v4, v3 quad_perm:[2,3,0,1] row_mask:0xf bank_mask:0xf bound_ctrl:1
	v_max_f32_e32 v4, v4, v4
	v_max_f32_e32 v3, v3, v4
	s_nop 1
	v_mov_b32_dpp v4, v3 row_half_mirror row_mask:0xf bank_mask:0xf bound_ctrl:1
	v_max_f32_e32 v4, v4, v4
	v_max_f32_e32 v3, v3, v4
	s_nop 1
	v_mov_b32_dpp v4, v3 row_mirror row_mask:0xf bank_mask:0xf bound_ctrl:1
	v_max_f32_e32 v4, v4, v4
	v_max_f32_e32 v3, v3, v4
	s_nop 0
	v_readlane_b32 s0, v3, 0
	v_readlane_b32 s1, v3, 16
	v_readlane_b32 s10, v3, 32
	v_readlane_b32 s11, v3, 48
	v_max_f32_e64 v3, s1, s1
	v_max_f32_e64 v4, s0, s0
	v_max_f32_e32 v3, v4, v3
	v_max_f32_e64 v4, s11, s11
	v_max_f32_e64 v5, s10, s10
	v_max_f32_e32 v4, v5, v4
	s_mov_b32 s0, 0xda24260
	v_max3_f32 v3, v3, v4, s0
	s_mov_b64 s[0:1], exec
	v_readlane_b32 s10, v254, 21
	v_readlane_b32 s11, v254, 22
	s_and_b64 s[10:11], s[0:1], s[10:11]
	s_mov_b64 exec, s[10:11]
	v_mul_f32_e32 v4, 0x3b888889, v3
	v_mov_b32_e32 v5, s93
	ds_write_b32 v5, v4 offset:14340
	s_or_b64 exec, exec, s[0:1]
	s_mov_b32 s10, 0x43700000
	v_div_scale_f32 v4, s[0:1], v3, v3, s10
	v_rcp_f32_e32 v5, v4
	s_mov_b32 s0, 0x7020c0c
	v_fma_f32 v6, -v4, v5, 1.0
	v_fmac_f32_e32 v5, v6, v5
	v_div_scale_f32 v6, vcc, s10, v3, s10
	v_mul_f32_e32 v7, v6, v5
	v_fma_f32 v8, -v4, v7, v6
	v_fmac_f32_e32 v7, v8, v5
	v_fma_f32 v4, -v4, v7, v6
	v_div_fmas_f32 v4, v4, v5, v7
	v_div_fixup_f32 v3, v4, v3, s10
	v_mul_f32_e32 v4, v3, v1
	v_mul_f32_e32 v5, v3, v2
	v_mov_b32_e32 v6, v155
	v_cvt_pk_fp8_f32 v6, v4, v5
	v_cvt_pk_f32_fp8_e32 v[4:5], v6
	v_fma_f32 v1, v3, v1, -v4
	v_fma_f32 v2, v3, v2, -v5
	v_mov_b32_e32 v4, v155
	v_cvt_pk_fp8_f32 v4, v1, v2
	ds_read2st64_b32 v[2:3], v178 offset0:6 offset1:7
	v_lshlrev_b32_e32 v1, 16, v6
	v_and_b32_e32 v1, 0xff0000, v1
	v_lshlrev_b32_e32 v5, 24, v4
	v_lshlrev_b32_e32 v4, 16, v4
	s_waitcnt lgkmcnt(0)
	v_or3_b32 v1, v2, v1, v5
	v_lshlrev_b32_e32 v2, 8, v6
	v_perm_b32 v2, v4, v2, s0
	v_or_b32_e32 v2, v2, v3
	ds_write2st64_b32 v178, v1, v2 offset0:8 offset1:9
	ds_read2st64_b32 v[2:3], v178 offset0:14 offset1:15
	ds_read2st64_b32 v[4:5], v178 offset0:16 offset1:17
	s_mov_b32 s0, 0x3e6d3388
	s_waitcnt lgkmcnt(0)
	v_fma_f32 v1, |v4|, s0, 1.0
	v_rcp_f32_e32 v1, v1
	v_cmp_gt_f32_e32 vcc, 0, v4
	v_fmamk_f32 v6, v1, 0x3f07dc22, v210
	v_fmaak_f32 v6, v1, v6, 0x3f35f0e3
	v_fmaak_f32 v6, v1, v6, 0xbe11a98e
	v_fmaak_f32 v6, v1, v6, 0x3e027906
	v_mul_f32_e32 v1, v1, v6
	v_mul_f32_e32 v6, v4, v4
	v_mul_f32_e32 v6, 0xbf38aa3b, v6
	v_exp_f32_e32 v6, v6
	s_nop 0
	v_mul_f32_e32 v1, v6, v1
	v_mul_f32_e32 v6, v4, v1
	v_fma_f32 v1, -v4, v1, v4
	v_cndmask_b32_e32 v1, v1, v6, vcc
	v_mul_f32_e32 v1, v2, v1
	v_fma_f32 v2, |v5|, s0, 1.0
	v_rcp_f32_e32 v2, v2
	v_cmp_gt_f32_e32 vcc, 0, v5
	v_fmamk_f32 v4, v2, 0x3f07dc22, v210
	v_fmaak_f32 v4, v2, v4, 0x3f35f0e3
	v_fmaak_f32 v4, v2, v4, 0xbe11a98e
	v_fmaak_f32 v4, v2, v4, 0x3e027906
	v_mul_f32_e32 v2, v2, v4
	v_mul_f32_e32 v4, v5, v5
	v_mul_f32_e32 v4, 0xbf38aa3b, v4
	v_exp_f32_e32 v4, v4
	s_nop 0
	v_mul_f32_e32 v2, v4, v2
	v_mul_f32_e32 v4, v5, v2
	v_fma_f32 v2, -v5, v2, v5
	v_cndmask_b32_e32 v2, v2, v4, vcc
	v_mul_f32_e32 v2, v3, v2
	v_max_f32_e64 v3, |v1|, |v2|
	s_nop 1
	v_mov_b32_dpp v4, v3 quad_perm:[1,0,3,2] row_mask:0xf bank_mask:0xf bound_ctrl:1
	v_max_f32_e32 v4, v4, v4
	v_max_f32_e32 v3, v3, v4
	s_nop 1
	v_mov_b32_dpp v4, v3 quad_perm:[2,3,0,1] row_mask:0xf bank_mask:0xf bound_ctrl:1
	v_max_f32_e32 v4, v4, v4
	v_max_f32_e32 v3, v3, v4
	s_nop 1
	v_mov_b32_dpp v4, v3 row_half_mirror row_mask:0xf bank_mask:0xf bound_ctrl:1
	v_max_f32_e32 v4, v4, v4
	v_max_f32_e32 v3, v3, v4
	s_nop 1
	v_mov_b32_dpp v4, v3 row_mirror row_mask:0xf bank_mask:0xf bound_ctrl:1
	v_max_f32_e32 v4, v4, v4
	v_max_f32_e32 v3, v3, v4
	s_nop 0
	v_readlane_b32 s0, v3, 0
	v_readlane_b32 s1, v3, 16
	v_readlane_b32 s10, v3, 32
	v_readlane_b32 s11, v3, 48
	v_max_f32_e64 v3, s1, s1
	v_max_f32_e64 v4, s0, s0
	v_max_f32_e32 v3, v4, v3
	v_max_f32_e64 v4, s11, s11
	v_max_f32_e64 v5, s10, s10
	v_max_f32_e32 v4, v5, v4
	s_mov_b32 s0, 0xda24260
	v_max3_f32 v3, v3, v4, s0
	s_mov_b64 s[0:1], exec
	v_readlane_b32 s10, v254, 21
	v_readlane_b32 s11, v254, 22
	s_and_b64 s[10:11], s[0:1], s[10:11]
	s_mov_b64 exec, s[10:11]
	v_mul_f32_e32 v4, 0x3b888889, v3
	v_mov_b32_e32 v5, s93
	ds_write_b32 v5, v4 offset:14344
	s_or_b64 exec, exec, s[0:1]
	s_mov_b32 s10, 0x43700000
	v_div_scale_f32 v4, s[0:1], v3, v3, s10
	v_rcp_f32_e32 v5, v4
	s_mov_b32 s0, 0x7020c0c
	v_fma_f32 v6, -v4, v5, 1.0
	v_fmac_f32_e32 v5, v6, v5
	v_div_scale_f32 v6, vcc, s10, v3, s10
	v_mul_f32_e32 v7, v6, v5
	v_fma_f32 v8, -v4, v7, v6
	v_fmac_f32_e32 v7, v8, v5
	v_fma_f32 v4, -v4, v7, v6
	v_div_fmas_f32 v4, v4, v5, v7
	v_div_fixup_f32 v3, v4, v3, s10
	v_mul_f32_e32 v4, v3, v1
	v_mul_f32_e32 v5, v3, v2
	v_mov_b32_e32 v6, v155
	v_cvt_pk_fp8_f32 v6, v4, v5
	v_cvt_pk_f32_fp8_e32 v[4:5], v6
	v_fma_f32 v1, v3, v1, -v4
	v_fma_f32 v2, v3, v2, -v5
	v_mov_b32_e32 v4, v155
	v_cvt_pk_fp8_f32 v4, v1, v2
	ds_read2st64_b32 v[2:3], v178 offset0:12 offset1:13
	v_lshlrev_b32_e32 v1, 16, v6
	v_and_b32_e32 v1, 0xff0000, v1
	v_lshlrev_b32_e32 v5, 24, v4
	v_lshlrev_b32_e32 v4, 16, v4
	s_waitcnt lgkmcnt(0)
	v_or3_b32 v1, v2, v1, v5
	v_lshlrev_b32_e32 v2, 8, v6
	v_perm_b32 v2, v4, v2, s0
	v_or_b32_e32 v2, v2, v3
	ds_write2st64_b32 v178, v1, v2 offset0:14 offset1:15
	ds_read2st64_b32 v[2:3], v178 offset0:20 offset1:21
	ds_read2st64_b32 v[4:5], v178 offset0:22 offset1:23
	s_mov_b32 s0, 0x3e6d3388
	s_waitcnt lgkmcnt(0)
	v_fma_f32 v1, |v4|, s0, 1.0
	v_rcp_f32_e32 v1, v1
	v_cmp_gt_f32_e32 vcc, 0, v4
	v_fmamk_f32 v6, v1, 0x3f07dc22, v210
	v_fmaak_f32 v6, v1, v6, 0x3f35f0e3
	v_fmaak_f32 v6, v1, v6, 0xbe11a98e
	v_fmaak_f32 v6, v1, v6, 0x3e027906
	v_mul_f32_e32 v1, v1, v6
	v_mul_f32_e32 v6, v4, v4
	v_mul_f32_e32 v6, 0xbf38aa3b, v6
	v_exp_f32_e32 v6, v6
	s_nop 0
	v_mul_f32_e32 v1, v6, v1
	v_mul_f32_e32 v6, v4, v1
	v_fma_f32 v1, -v4, v1, v4
	v_cndmask_b32_e32 v1, v1, v6, vcc
	v_mul_f32_e32 v1, v2, v1
	v_fma_f32 v2, |v5|, s0, 1.0
	v_rcp_f32_e32 v2, v2
	v_cmp_gt_f32_e32 vcc, 0, v5
	v_fmamk_f32 v4, v2, 0x3f07dc22, v210
	v_fmaak_f32 v4, v2, v4, 0x3f35f0e3
	v_fmaak_f32 v4, v2, v4, 0xbe11a98e
	v_fmaak_f32 v4, v2, v4, 0x3e027906
	v_mul_f32_e32 v2, v2, v4
	v_mul_f32_e32 v4, v5, v5
	v_mul_f32_e32 v4, 0xbf38aa3b, v4
	v_exp_f32_e32 v4, v4
	s_nop 0
	v_mul_f32_e32 v2, v4, v2
	v_mul_f32_e32 v4, v5, v2
	v_fma_f32 v2, -v5, v2, v5
	v_cndmask_b32_e32 v2, v2, v4, vcc
	v_mul_f32_e32 v2, v3, v2
	v_max_f32_e64 v3, |v1|, |v2|
	s_nop 1
	v_mov_b32_dpp v4, v3 quad_perm:[1,0,3,2] row_mask:0xf bank_mask:0xf bound_ctrl:1
	v_max_f32_e32 v4, v4, v4
	v_max_f32_e32 v3, v3, v4
	s_nop 1
	v_mov_b32_dpp v4, v3 quad_perm:[2,3,0,1] row_mask:0xf bank_mask:0xf bound_ctrl:1
	v_max_f32_e32 v4, v4, v4
	v_max_f32_e32 v3, v3, v4
	s_nop 1
	v_mov_b32_dpp v4, v3 row_half_mirror row_mask:0xf bank_mask:0xf bound_ctrl:1
	v_max_f32_e32 v4, v4, v4
	v_max_f32_e32 v3, v3, v4
	s_nop 1
	v_mov_b32_dpp v4, v3 row_mirror row_mask:0xf bank_mask:0xf bound_ctrl:1
	v_max_f32_e32 v4, v4, v4
	v_max_f32_e32 v3, v3, v4
	s_nop 0
	v_readlane_b32 s0, v3, 0
	v_readlane_b32 s1, v3, 16
	v_readlane_b32 s10, v3, 32
	v_readlane_b32 s11, v3, 48
	v_max_f32_e64 v3, s1, s1
	v_max_f32_e64 v4, s0, s0
	v_max_f32_e32 v3, v4, v3
	v_max_f32_e64 v4, s11, s11
	v_max_f32_e64 v5, s10, s10
	v_max_f32_e32 v4, v5, v4
	s_mov_b32 s0, 0xda24260
	v_max3_f32 v3, v3, v4, s0
	s_mov_b64 s[0:1], exec
	v_readlane_b32 s10, v254, 21
	v_readlane_b32 s11, v254, 22
	s_and_b64 s[10:11], s[0:1], s[10:11]
	s_mov_b64 exec, s[10:11]
	v_mul_f32_e32 v4, 0x3b888889, v3
	v_mov_b32_e32 v5, s93
	ds_write_b32 v5, v4 offset:14348
	s_or_b64 exec, exec, s[0:1]
	s_mov_b32 s10, 0x43700000
	v_div_scale_f32 v4, s[0:1], v3, v3, s10
	v_rcp_f32_e32 v5, v4
	s_mov_b32 s0, 0x7020c0c
	v_fma_f32 v6, -v4, v5, 1.0
	v_fmac_f32_e32 v5, v6, v5
	v_div_scale_f32 v6, vcc, s10, v3, s10
	v_mul_f32_e32 v7, v6, v5
	v_fma_f32 v8, -v4, v7, v6
	v_fmac_f32_e32 v7, v8, v5
	v_fma_f32 v4, -v4, v7, v6
	v_div_fmas_f32 v4, v4, v5, v7
	v_div_fixup_f32 v3, v4, v3, s10
	v_mul_f32_e32 v4, v3, v1
	v_mul_f32_e32 v5, v3, v2
	v_mov_b32_e32 v6, v155
	v_cvt_pk_fp8_f32 v6, v4, v5
	v_cvt_pk_f32_fp8_e32 v[4:5], v6
	v_fma_f32 v1, v3, v1, -v4
	v_fma_f32 v2, v3, v2, -v5
	v_mov_b32_e32 v4, v155
	v_cvt_pk_fp8_f32 v4, v1, v2
	ds_read2st64_b32 v[2:3], v178 offset0:18 offset1:19
	v_lshlrev_b32_e32 v1, 16, v6
	v_and_b32_e32 v1, 0xff0000, v1
	v_lshlrev_b32_e32 v5, 24, v4
	v_lshlrev_b32_e32 v4, 16, v4
	s_waitcnt lgkmcnt(0)
	v_or3_b32 v1, v2, v1, v5
	v_lshlrev_b32_e32 v2, 8, v6
	v_perm_b32 v2, v4, v2, s0
	v_or_b32_e32 v2, v2, v3
	ds_write2st64_b32 v178, v1, v2 offset0:20 offset1:21
	ds_read2st64_b32 v[2:3], v178 offset0:26 offset1:27
	ds_read2st64_b32 v[4:5], v178 offset0:28 offset1:29
	s_mov_b32 s0, 0x3e6d3388
	s_waitcnt lgkmcnt(0)
	v_fma_f32 v1, |v4|, s0, 1.0
	v_rcp_f32_e32 v1, v1
	v_cmp_gt_f32_e32 vcc, 0, v4
	v_fmamk_f32 v6, v1, 0x3f07dc22, v210
	v_fmaak_f32 v6, v1, v6, 0x3f35f0e3
	v_fmaak_f32 v6, v1, v6, 0xbe11a98e
	v_fmaak_f32 v6, v1, v6, 0x3e027906
	v_mul_f32_e32 v1, v1, v6
	v_mul_f32_e32 v6, v4, v4
	v_mul_f32_e32 v6, 0xbf38aa3b, v6
	v_exp_f32_e32 v6, v6
	s_nop 0
	v_mul_f32_e32 v1, v6, v1
	v_mul_f32_e32 v6, v4, v1
	v_fma_f32 v1, -v4, v1, v4
	v_cndmask_b32_e32 v1, v1, v6, vcc
	v_mul_f32_e32 v1, v2, v1
	v_fma_f32 v2, |v5|, s0, 1.0
	v_rcp_f32_e32 v2, v2
	v_cmp_gt_f32_e32 vcc, 0, v5
	v_fmamk_f32 v4, v2, 0x3f07dc22, v210
	v_fmaak_f32 v4, v2, v4, 0x3f35f0e3
	v_fmaak_f32 v4, v2, v4, 0xbe11a98e
	v_fmaak_f32 v4, v2, v4, 0x3e027906
	v_mul_f32_e32 v2, v2, v4
	v_mul_f32_e32 v4, v5, v5
	v_mul_f32_e32 v4, 0xbf38aa3b, v4
	v_exp_f32_e32 v4, v4
	s_nop 0
	v_mul_f32_e32 v2, v4, v2
	v_mul_f32_e32 v4, v5, v2
	v_fma_f32 v2, -v5, v2, v5
	v_cndmask_b32_e32 v2, v2, v4, vcc
	v_mul_f32_e32 v2, v3, v2
	v_max_f32_e64 v3, |v1|, |v2|
	s_nop 1
	v_mov_b32_dpp v4, v3 quad_perm:[1,0,3,2] row_mask:0xf bank_mask:0xf bound_ctrl:1
	v_max_f32_e32 v4, v4, v4
	v_max_f32_e32 v3, v3, v4
	s_nop 1
	v_mov_b32_dpp v4, v3 quad_perm:[2,3,0,1] row_mask:0xf bank_mask:0xf bound_ctrl:1
	v_max_f32_e32 v4, v4, v4
	v_max_f32_e32 v3, v3, v4
	s_nop 1
	v_mov_b32_dpp v4, v3 row_half_mirror row_mask:0xf bank_mask:0xf bound_ctrl:1
	v_max_f32_e32 v4, v4, v4
	v_max_f32_e32 v3, v3, v4
	s_nop 1
	v_mov_b32_dpp v4, v3 row_mirror row_mask:0xf bank_mask:0xf bound_ctrl:1
	v_max_f32_e32 v4, v4, v4
	v_max_f32_e32 v3, v3, v4
	s_nop 0
	v_readlane_b32 s0, v3, 0
	v_readlane_b32 s1, v3, 16
	v_readlane_b32 s10, v3, 32
	v_readlane_b32 s11, v3, 48
	v_max_f32_e64 v3, s1, s1
	v_max_f32_e64 v4, s0, s0
	v_max_f32_e32 v3, v4, v3
	v_max_f32_e64 v4, s11, s11
	v_max_f32_e64 v5, s10, s10
	v_max_f32_e32 v4, v5, v4
	s_mov_b32 s0, 0xda24260
	v_max3_f32 v3, v3, v4, s0
	s_mov_b64 s[0:1], exec
	v_readlane_b32 s10, v254, 21
	v_readlane_b32 s11, v254, 22
	s_and_b64 s[10:11], s[0:1], s[10:11]
	s_mov_b64 exec, s[10:11]
	v_mul_f32_e32 v4, 0x3b888889, v3
	v_mov_b32_e32 v5, s93
	ds_write_b32 v5, v4 offset:14352
	s_or_b64 exec, exec, s[0:1]
	s_mov_b32 s10, 0x43700000
	v_div_scale_f32 v4, s[0:1], v3, v3, s10
	v_rcp_f32_e32 v5, v4
	s_mov_b32 s0, 0x7020c0c
	v_fma_f32 v6, -v4, v5, 1.0
	v_fmac_f32_e32 v5, v6, v5
	v_div_scale_f32 v6, vcc, s10, v3, s10
	v_mul_f32_e32 v7, v6, v5
	v_fma_f32 v8, -v4, v7, v6
	v_fmac_f32_e32 v7, v8, v5
	v_fma_f32 v4, -v4, v7, v6
	v_div_fmas_f32 v4, v4, v5, v7
	v_div_fixup_f32 v3, v4, v3, s10
	v_mul_f32_e32 v4, v3, v1
	v_mul_f32_e32 v5, v3, v2
	v_mov_b32_e32 v6, v155
	v_cvt_pk_fp8_f32 v6, v4, v5
	v_cvt_pk_f32_fp8_e32 v[4:5], v6
	v_fma_f32 v1, v3, v1, -v4
	v_fma_f32 v2, v3, v2, -v5
	v_mov_b32_e32 v4, v155
	v_cvt_pk_fp8_f32 v4, v1, v2
	ds_read2st64_b32 v[2:3], v178 offset0:24 offset1:25
	v_lshlrev_b32_e32 v1, 16, v6
	v_and_b32_e32 v1, 0xff0000, v1
	v_lshlrev_b32_e32 v5, 24, v4
	v_lshlrev_b32_e32 v4, 16, v4
	s_waitcnt lgkmcnt(0)
	v_or3_b32 v1, v2, v1, v5
	v_lshlrev_b32_e32 v2, 8, v6
	v_perm_b32 v2, v4, v2, s0
	v_or_b32_e32 v2, v2, v3
	ds_write2st64_b32 v178, v1, v2 offset0:26 offset1:27
	ds_read2st64_b32 v[2:3], v178 offset0:32 offset1:33
	ds_read2st64_b32 v[4:5], v178 offset0:34 offset1:35
	s_mov_b32 s0, 0x3e6d3388
	s_waitcnt lgkmcnt(0)
	v_fma_f32 v1, |v4|, s0, 1.0
	v_rcp_f32_e32 v1, v1
	v_cmp_gt_f32_e32 vcc, 0, v4
	v_fmamk_f32 v6, v1, 0x3f07dc22, v210
	v_fmaak_f32 v6, v1, v6, 0x3f35f0e3
	v_fmaak_f32 v6, v1, v6, 0xbe11a98e
	v_fmaak_f32 v6, v1, v6, 0x3e027906
	v_mul_f32_e32 v1, v1, v6
	v_mul_f32_e32 v6, v4, v4
	v_mul_f32_e32 v6, 0xbf38aa3b, v6
	v_exp_f32_e32 v6, v6
	s_nop 0
	v_mul_f32_e32 v1, v6, v1
	v_mul_f32_e32 v6, v4, v1
	v_fma_f32 v1, -v4, v1, v4
	v_cndmask_b32_e32 v1, v1, v6, vcc
	v_mul_f32_e32 v1, v2, v1
	v_fma_f32 v2, |v5|, s0, 1.0
	v_rcp_f32_e32 v2, v2
	v_cmp_gt_f32_e32 vcc, 0, v5
	v_fmamk_f32 v4, v2, 0x3f07dc22, v210
	v_fmaak_f32 v4, v2, v4, 0x3f35f0e3
	v_fmaak_f32 v4, v2, v4, 0xbe11a98e
	v_fmaak_f32 v4, v2, v4, 0x3e027906
	v_mul_f32_e32 v2, v2, v4
	v_mul_f32_e32 v4, v5, v5
	v_mul_f32_e32 v4, 0xbf38aa3b, v4
	v_exp_f32_e32 v4, v4
	s_nop 0
	v_mul_f32_e32 v2, v4, v2
	v_mul_f32_e32 v4, v5, v2
	v_fma_f32 v2, -v5, v2, v5
	v_cndmask_b32_e32 v2, v2, v4, vcc
	v_mul_f32_e32 v2, v3, v2
	v_max_f32_e64 v3, |v1|, |v2|
	s_nop 1
	v_mov_b32_dpp v4, v3 quad_perm:[1,0,3,2] row_mask:0xf bank_mask:0xf bound_ctrl:1
	v_max_f32_e32 v4, v4, v4
	v_max_f32_e32 v3, v3, v4
	s_nop 1
	v_mov_b32_dpp v4, v3 quad_perm:[2,3,0,1] row_mask:0xf bank_mask:0xf bound_ctrl:1
	v_max_f32_e32 v4, v4, v4
	v_max_f32_e32 v3, v3, v4
	s_nop 1
	v_mov_b32_dpp v4, v3 row_half_mirror row_mask:0xf bank_mask:0xf bound_ctrl:1
	v_max_f32_e32 v4, v4, v4
	v_max_f32_e32 v3, v3, v4
	s_nop 1
	v_mov_b32_dpp v4, v3 row_mirror row_mask:0xf bank_mask:0xf bound_ctrl:1
	v_max_f32_e32 v4, v4, v4
	v_max_f32_e32 v3, v3, v4
	s_nop 0
	v_readlane_b32 s0, v3, 0
	v_readlane_b32 s1, v3, 16
	v_readlane_b32 s10, v3, 32
	v_readlane_b32 s11, v3, 48
	v_max_f32_e64 v3, s1, s1
	v_max_f32_e64 v4, s0, s0
	v_max_f32_e32 v3, v4, v3
	v_max_f32_e64 v4, s11, s11
	v_max_f32_e64 v5, s10, s10
	v_max_f32_e32 v4, v5, v4
	s_mov_b32 s0, 0xda24260
	v_max3_f32 v3, v3, v4, s0
	s_mov_b64 s[0:1], exec
	v_readlane_b32 s10, v254, 21
	v_readlane_b32 s11, v254, 22
	s_and_b64 s[10:11], s[0:1], s[10:11]
	s_mov_b64 exec, s[10:11]
	v_mul_f32_e32 v4, 0x3b888889, v3
	v_mov_b32_e32 v5, s93
	ds_write_b32 v5, v4 offset:14356
	s_or_b64 exec, exec, s[0:1]
	s_mov_b32 s10, 0x43700000
	v_div_scale_f32 v4, s[0:1], v3, v3, s10
	v_rcp_f32_e32 v5, v4
	s_mov_b32 s0, 0x7020c0c
	v_fma_f32 v6, -v4, v5, 1.0
	v_fmac_f32_e32 v5, v6, v5
	v_div_scale_f32 v6, vcc, s10, v3, s10
	v_mul_f32_e32 v7, v6, v5
	v_fma_f32 v8, -v4, v7, v6
	v_fmac_f32_e32 v7, v8, v5
	v_fma_f32 v4, -v4, v7, v6
	v_div_fmas_f32 v4, v4, v5, v7
	v_div_fixup_f32 v3, v4, v3, s10
	v_mul_f32_e32 v4, v3, v1
	v_mul_f32_e32 v5, v3, v2
	v_mov_b32_e32 v6, v155
	v_cvt_pk_fp8_f32 v6, v4, v5
	v_cvt_pk_f32_fp8_e32 v[4:5], v6
	v_fma_f32 v1, v3, v1, -v4
	v_fma_f32 v2, v3, v2, -v5
	v_mov_b32_e32 v4, v155
	v_cvt_pk_fp8_f32 v4, v1, v2
	ds_read2st64_b32 v[2:3], v178 offset0:30 offset1:31
	v_lshlrev_b32_e32 v1, 16, v6
	v_and_b32_e32 v1, 0xff0000, v1
	v_lshlrev_b32_e32 v5, 24, v4
	v_lshlrev_b32_e32 v4, 16, v4
	s_waitcnt lgkmcnt(0)
	v_or3_b32 v1, v2, v1, v5
	v_lshlrev_b32_e32 v2, 8, v6
	v_perm_b32 v2, v4, v2, s0
	v_or_b32_e32 v2, v2, v3
	ds_write2st64_b32 v178, v1, v2 offset0:32 offset1:33
	ds_read2st64_b32 v[2:3], v178 offset0:38 offset1:39
	ds_read2st64_b32 v[4:5], v178 offset0:40 offset1:41
	s_mov_b32 s0, 0x3e6d3388
	s_waitcnt lgkmcnt(0)
	v_fma_f32 v1, |v4|, s0, 1.0
	v_rcp_f32_e32 v1, v1
	v_cmp_gt_f32_e32 vcc, 0, v4
	v_fmamk_f32 v6, v1, 0x3f07dc22, v210
	v_fmaak_f32 v6, v1, v6, 0x3f35f0e3
	v_fmaak_f32 v6, v1, v6, 0xbe11a98e
	v_fmaak_f32 v6, v1, v6, 0x3e027906
	v_mul_f32_e32 v1, v1, v6
	v_mul_f32_e32 v6, v4, v4
	v_mul_f32_e32 v6, 0xbf38aa3b, v6
	v_exp_f32_e32 v6, v6
	s_nop 0
	v_mul_f32_e32 v1, v6, v1
	v_mul_f32_e32 v6, v4, v1
	v_fma_f32 v1, -v4, v1, v4
	v_cndmask_b32_e32 v1, v1, v6, vcc
	v_mul_f32_e32 v1, v2, v1
	v_fma_f32 v2, |v5|, s0, 1.0
	v_rcp_f32_e32 v2, v2
	v_cmp_gt_f32_e32 vcc, 0, v5
	v_fmamk_f32 v4, v2, 0x3f07dc22, v210
	v_fmaak_f32 v4, v2, v4, 0x3f35f0e3
	v_fmaak_f32 v4, v2, v4, 0xbe11a98e
	v_fmaak_f32 v4, v2, v4, 0x3e027906
	v_mul_f32_e32 v2, v2, v4
	v_mul_f32_e32 v4, v5, v5
	v_mul_f32_e32 v4, 0xbf38aa3b, v4
	v_exp_f32_e32 v4, v4
	s_nop 0
	v_mul_f32_e32 v2, v4, v2
	v_mul_f32_e32 v4, v5, v2
	v_fma_f32 v2, -v5, v2, v5
	v_cndmask_b32_e32 v2, v2, v4, vcc
	v_mul_f32_e32 v2, v3, v2
	v_max_f32_e64 v3, |v1|, |v2|
	s_nop 1
	v_mov_b32_dpp v4, v3 quad_perm:[1,0,3,2] row_mask:0xf bank_mask:0xf bound_ctrl:1
	v_max_f32_e32 v4, v4, v4
	v_max_f32_e32 v3, v3, v4
	s_nop 1
	v_mov_b32_dpp v4, v3 quad_perm:[2,3,0,1] row_mask:0xf bank_mask:0xf bound_ctrl:1
	v_max_f32_e32 v4, v4, v4
	v_max_f32_e32 v3, v3, v4
	s_nop 1
	v_mov_b32_dpp v4, v3 row_half_mirror row_mask:0xf bank_mask:0xf bound_ctrl:1
	v_max_f32_e32 v4, v4, v4
	v_max_f32_e32 v3, v3, v4
	s_nop 1
	v_mov_b32_dpp v4, v3 row_mirror row_mask:0xf bank_mask:0xf bound_ctrl:1
	v_max_f32_e32 v4, v4, v4
	v_max_f32_e32 v3, v3, v4
	s_nop 0
	v_readlane_b32 s0, v3, 0
	v_readlane_b32 s1, v3, 16
	v_readlane_b32 s10, v3, 32
	v_readlane_b32 s11, v3, 48
	v_max_f32_e64 v3, s1, s1
	v_max_f32_e64 v4, s0, s0
	v_max_f32_e32 v3, v4, v3
	v_max_f32_e64 v4, s11, s11
	v_max_f32_e64 v5, s10, s10
	v_max_f32_e32 v4, v5, v4
	s_mov_b32 s0, 0xda24260
	v_max3_f32 v3, v3, v4, s0
	s_mov_b64 s[0:1], exec
	v_readlane_b32 s10, v254, 21
	v_readlane_b32 s11, v254, 22
	s_and_b64 s[10:11], s[0:1], s[10:11]
	s_mov_b64 exec, s[10:11]
	v_mul_f32_e32 v4, 0x3b888889, v3
	v_mov_b32_e32 v5, s93
	ds_write_b32 v5, v4 offset:14360
	s_or_b64 exec, exec, s[0:1]
	s_mov_b32 s10, 0x43700000
	v_div_scale_f32 v4, s[0:1], v3, v3, s10
	v_rcp_f32_e32 v5, v4
	s_mov_b32 s0, 0x7020c0c
	v_fma_f32 v6, -v4, v5, 1.0
	v_fmac_f32_e32 v5, v6, v5
	v_div_scale_f32 v6, vcc, s10, v3, s10
	v_mul_f32_e32 v7, v6, v5
	v_fma_f32 v8, -v4, v7, v6
	v_fmac_f32_e32 v7, v8, v5
	v_fma_f32 v4, -v4, v7, v6
	v_div_fmas_f32 v4, v4, v5, v7
	v_div_fixup_f32 v3, v4, v3, s10
	v_mul_f32_e32 v4, v3, v1
	v_mul_f32_e32 v5, v3, v2
	v_mov_b32_e32 v6, v155
	v_cvt_pk_fp8_f32 v6, v4, v5
	v_cvt_pk_f32_fp8_e32 v[4:5], v6
	v_fma_f32 v1, v3, v1, -v4
	v_fma_f32 v2, v3, v2, -v5
	v_mov_b32_e32 v4, v155
	v_cvt_pk_fp8_f32 v4, v1, v2
	ds_read2st64_b32 v[2:3], v178 offset0:36 offset1:37
	v_lshlrev_b32_e32 v1, 16, v6
	v_and_b32_e32 v1, 0xff0000, v1
	v_lshlrev_b32_e32 v5, 24, v4
	v_lshlrev_b32_e32 v4, 16, v4
	s_waitcnt lgkmcnt(0)
	v_or3_b32 v1, v2, v1, v5
	v_lshlrev_b32_e32 v2, 8, v6
	v_perm_b32 v2, v4, v2, s0
	v_or_b32_e32 v2, v2, v3
	ds_write2st64_b32 v178, v1, v2 offset0:38 offset1:39
	ds_read2st64_b32 v[2:3], v178 offset0:44 offset1:45
	ds_read2st64_b32 v[4:5], v178 offset0:46 offset1:47
	s_mov_b32 s0, 0x3e6d3388
	s_waitcnt lgkmcnt(0)
	v_fma_f32 v1, |v4|, s0, 1.0
	v_rcp_f32_e32 v1, v1
	v_cmp_gt_f32_e32 vcc, 0, v4
	v_fmamk_f32 v6, v1, 0x3f07dc22, v210
	v_fmaak_f32 v6, v1, v6, 0x3f35f0e3
	v_fmaak_f32 v6, v1, v6, 0xbe11a98e
	v_fmaak_f32 v6, v1, v6, 0x3e027906
	v_mul_f32_e32 v1, v1, v6
	v_mul_f32_e32 v6, v4, v4
	v_mul_f32_e32 v6, 0xbf38aa3b, v6
	v_exp_f32_e32 v6, v6
	s_nop 0
	v_mul_f32_e32 v1, v6, v1
	v_mul_f32_e32 v6, v4, v1
	v_fma_f32 v1, -v4, v1, v4
	v_cndmask_b32_e32 v1, v1, v6, vcc
	v_mul_f32_e32 v1, v2, v1
	v_fma_f32 v2, |v5|, s0, 1.0
	v_rcp_f32_e32 v2, v2
	v_cmp_gt_f32_e32 vcc, 0, v5
	v_fmamk_f32 v4, v2, 0x3f07dc22, v210
	v_fmaak_f32 v4, v2, v4, 0x3f35f0e3
	v_fmaak_f32 v4, v2, v4, 0xbe11a98e
	v_fmaak_f32 v4, v2, v4, 0x3e027906
	v_mul_f32_e32 v2, v2, v4
	v_mul_f32_e32 v4, v5, v5
	v_mul_f32_e32 v4, 0xbf38aa3b, v4
	v_exp_f32_e32 v4, v4
	s_nop 0
	v_mul_f32_e32 v2, v4, v2
	v_mul_f32_e32 v4, v5, v2
	v_fma_f32 v2, -v5, v2, v5
	v_cndmask_b32_e32 v2, v2, v4, vcc
	v_mul_f32_e32 v2, v3, v2
	v_max_f32_e64 v3, |v1|, |v2|
	s_nop 1
	v_mov_b32_dpp v4, v3 quad_perm:[1,0,3,2] row_mask:0xf bank_mask:0xf bound_ctrl:1
	v_max_f32_e32 v4, v4, v4
	v_max_f32_e32 v3, v3, v4
	s_nop 1
	v_mov_b32_dpp v4, v3 quad_perm:[2,3,0,1] row_mask:0xf bank_mask:0xf bound_ctrl:1
	v_max_f32_e32 v4, v4, v4
	v_max_f32_e32 v3, v3, v4
	s_nop 1
	v_mov_b32_dpp v4, v3 row_half_mirror row_mask:0xf bank_mask:0xf bound_ctrl:1
	v_max_f32_e32 v4, v4, v4
	v_max_f32_e32 v3, v3, v4
	s_nop 1
	v_mov_b32_dpp v4, v3 row_mirror row_mask:0xf bank_mask:0xf bound_ctrl:1
	v_max_f32_e32 v4, v4, v4
	v_max_f32_e32 v3, v3, v4
	s_nop 0
	v_readlane_b32 s0, v3, 0
	v_readlane_b32 s1, v3, 16
	v_readlane_b32 s10, v3, 32
	v_readlane_b32 s11, v3, 48
	v_max_f32_e64 v3, s1, s1
	v_max_f32_e64 v4, s0, s0
	v_max_f32_e32 v3, v4, v3
	v_max_f32_e64 v4, s11, s11
	v_max_f32_e64 v5, s10, s10
	v_max_f32_e32 v4, v5, v4
	s_mov_b32 s0, 0xda24260
	v_max3_f32 v3, v3, v4, s0
	s_mov_b64 s[0:1], exec
	v_readlane_b32 s10, v254, 21
	v_readlane_b32 s11, v254, 22
	s_and_b64 s[10:11], s[0:1], s[10:11]
	s_mov_b64 exec, s[10:11]
	v_mul_f32_e32 v4, 0x3b888889, v3
	v_mov_b32_e32 v5, s93
	ds_write_b32 v5, v4 offset:14364
	s_or_b64 exec, exec, s[0:1]
	s_mov_b32 s10, 0x43700000
	v_div_scale_f32 v4, s[0:1], v3, v3, s10
	v_rcp_f32_e32 v5, v4
	s_mov_b32 s0, 0x7020c0c
	v_readlane_b32 s12, v254, 29
	v_fma_f32 v6, -v4, v5, 1.0
	v_fmac_f32_e32 v5, v6, v5
	v_div_scale_f32 v6, vcc, s10, v3, s10
	v_mul_f32_e32 v7, v6, v5
	v_fma_f32 v8, -v4, v7, v6
	v_fmac_f32_e32 v7, v8, v5
	v_fma_f32 v4, -v4, v7, v6
	v_div_fmas_f32 v4, v4, v5, v7
	v_div_fixup_f32 v3, v4, v3, s10
	v_mul_f32_e32 v4, v3, v1
	v_mul_f32_e32 v5, v3, v2
	v_mov_b32_e32 v6, v155
	v_cvt_pk_fp8_f32 v6, v4, v5
	s_mov_b32 s10, 0
	v_cvt_pk_f32_fp8_e32 v[4:5], v6
	v_fma_f32 v1, v3, v1, -v4
	v_fma_f32 v2, v3, v2, -v5
	v_mov_b32_e32 v4, v155
	v_cvt_pk_fp8_f32 v4, v1, v2
	ds_read2st64_b32 v[2:3], v178 offset0:42 offset1:43
	v_lshlrev_b32_e32 v1, 16, v6
	v_and_b32_e32 v1, 0xff0000, v1
	v_lshlrev_b32_e32 v5, 24, v4
	v_lshlrev_b32_e32 v4, 16, v4
	s_waitcnt lgkmcnt(0)
	v_or3_b32 v1, v2, v1, v5
	v_lshlrev_b32_e32 v2, 8, v6
	v_perm_b32 v2, v4, v2, s0
	s_add_i32 s0, s40, 0xffffe000
	s_lshr_b32 s0, s0, 12
	s_add_i32 s0, s0, 1
	s_cmpk_gt_i32 s40, 0x1fff
	s_cselect_b32 s11, s0, 0
	v_readlane_b32 s0, v254, 20
	s_mul_i32 s0, s0, 3
	s_add_i32 s11, s11, s0
	v_or_b32_e32 v2, v2, v3
	s_mul_i32 s1, s11, 0x6000
	ds_write2st64_b32 v178, v1, v2 offset0:44 offset1:45
	s_mul_hi_u32 s0, s11, 0x6000
	s_add_u32 s1, s12, s1
	v_readlane_b32 s12, v254, 30
	s_waitcnt lgkmcnt(0)
	s_addc_u32 s12, s12, s0
	s_add_u32 s0, s1, 0x5000
	s_addc_u32 s1, s12, 0
